# P4: S5 chunk scan moved to workgroups 128-255 (two waves each), which run one sweep less of the mixer scan
# speedup vs baseline: 1.0046x; 1.0046x over previous
.LBB0_754:
	s_or_b64 exec, exec, s[0:1]
	s_mov_b64 s[4:5], s[78:79]
	s_mov_b64 s[6:7], s[78:79]
	s_mov_b64 s[8:9], s[78:79]
	s_waitcnt vmcnt(11) lgkmcnt(0)
	v_mov_b32_e32 v0, v224
	s_movk_i32 s0, 0x80
	s_barrier
	s_nop 0
	v_cmp_gt_i32_e32 vcc, s0, v0
	s_and_saveexec_b64 s[0:1], vcc
	s_cbranch_execz .LBB0_760
	v_readlane_b32 s10, v252, 29
	s_nop 1
	v_add_u32_e32 v1, s10, v0
	v_cmp_gt_i32_e32 vcc, s89, v1
	s_and_b64 exec, exec, vcc
	s_cbranch_execz .LBB0_760
	s_cmp_lt_u32 s2, 0x80
	s_cbranch_scc1 .LBB0_760
	s_load_dwordx2 s[4:5], s[78:79], 0x100
	v_and_b32_e32 v188, 15, v224
	v_bfe_u32 v189, v224, 4, 1
	v_bfe_u32 v190, v224, 5, 1
	v_readfirstlane_b32 s6, v224
	s_lshr_b32 s6, s6, 6
	s_sub_u32 s7, s2, 0x80
	s_lshl_b32 s7, s7, 1
	s_add_u32 s8, s7, s6
	s_and_b32 s6, s8, 7
	s_lshl_b32 s6, s6, 1
	s_lshr_b32 s7, s8, 3
	s_mul_i32 s7, s7, 72
	v_add_u32_e32 v190, s6, v190
	v_lshl_add_u32 v50, v190, 1, v189
	v_lshlrev_b32_e32 v50, 6, v50
	v_lshl_add_u32 v50, v188, 2, v50
	v_mul_u32_u24_e32 v50, 0x108, v50
	s_mul_i32 s10, s80, 0x1c4000
	s_waitcnt lgkmcnt(0)
	s_add_u32 s10, s4, s10
	s_addc_u32 s11, s5, 0
	s_add_u32 s10, s10, 0x6040100
	s_addc_u32 s11, s11, 0
	global_load_dwordx2 v[164:165], v50, s[10:11]
	global_load_dwordx2 v[166:167], v50, s[10:11] offset:264
	global_load_dwordx2 v[168:169], v50, s[10:11] offset:528
	global_load_dwordx2 v[170:171], v50, s[10:11] offset:792
	v_mul_u32_u24_e32 v190, 0x900, v190
	v_add_u32_e32 v190, s7, v190
	v_mul_u32_u24_e32 v160, 7, v189
	v_add_u32_e32 v190, v190, v160
	v_lshlrev_b32_e32 v50, 10, v190
	v_lshl_add_u32 v50, v189, 9, v50
	v_lshl_add_u32 v50, v188, 4, v50
	v_mul_u32_u24_e32 v51, 0x600, v190
	v_lshl_add_u32 v51, v189, 8, v51
	v_lshl_add_u32 v51, v188, 3, v51
	v_add_u32_e32 v51, 0x400, v51
	v_sub_u32_e32 v116, 0, v189
	v_lshlrev_b32_e32 v116, 1, v116
	v_add_u32_e32 v116, 1, v116
	v_mul_i32_i24_e32 v117, 0x600, v116
	v_lshlrev_b32_e32 v116, 10, v116
	v_mul_u32_u24_e32 v160, 0x12000, v189
	v_mul_u32_u24_e32 v162, 0x1b000, v189
	s_add_u32 s6, s4, 0x38f14000
	s_addc_u32 s7, s5, 0
	s_add_u32 s8, s4, 0x29314000
	s_addc_u32 s9, s5, 0
	global_load_dwordx4 v[0:3], v50, s[6:7]
	global_load_dwordx4 v[4:7], v50, s[6:7] offset:256
	v_add_u32_e32 v50, v50, v116
	global_load_dwordx4 v[8:11], v50, s[6:7]
	global_load_dwordx4 v[12:15], v50, s[6:7] offset:256
	v_add_u32_e32 v50, v50, v116
	global_load_dwordx4 v[16:19], v50, s[6:7]
	global_load_dwordx4 v[20:23], v50, s[6:7] offset:256
	v_add_u32_e32 v50, v50, v116
	global_load_dwordx4 v[24:27], v50, s[6:7]
	global_load_dwordx4 v[28:31], v50, s[6:7] offset:256
	v_add_u32_e32 v50, v50, v116
	global_load_dwordx4 v[32:35], v50, s[6:7]
	global_load_dwordx4 v[36:39], v50, s[6:7] offset:256
	v_add_u32_e32 v50, v50, v116
	global_load_dwordx4 v[40:43], v50, s[6:7]
	global_load_dwordx4 v[44:47], v50, s[6:7] offset:256
	v_add_u32_e32 v50, v50, v116
	global_load_dwordx4 v[52:55], v50, s[6:7]
	global_load_dwordx4 v[56:59], v50, s[6:7] offset:256
	v_add_u32_e32 v50, v50, v116
	global_load_dwordx4 v[60:63], v50, s[6:7]
	global_load_dwordx4 v[64:67], v50, s[6:7] offset:256
	v_add_u32_e32 v50, v50, v116
	v_add_u32_e32 v50, v50, v160
	global_load_dwordx4 v[68:71], v50, s[6:7]
	global_load_dwordx4 v[72:75], v50, s[6:7] offset:256
	v_add_u32_e32 v50, v50, v116
	global_load_dwordx4 v[76:79], v50, s[6:7]
	global_load_dwordx4 v[80:83], v50, s[6:7] offset:256
	v_add_u32_e32 v50, v50, v116
	s_waitcnt vmcnt(20)
	v_mov_b32_e32 v108, v164
	v_mov_b32_e32 v112, v165
	v_mov_b32_e32 v109, v166
	v_mov_b32_e32 v113, v167
	v_mov_b32_e32 v110, v168
	v_mov_b32_e32 v114, v169
	v_mov_b32_e32 v111, v170
	v_mov_b32_e32 v115, v171
	v_mov_b32_e32 v92, 0
	v_mov_b32_e32 v93, 0
	v_mov_b32_e32 v94, 0
	v_mov_b32_e32 v95, 0
	v_mov_b32_e32 v96, 0
	v_mov_b32_e32 v97, 0
	v_mov_b32_e32 v98, 0
	v_mov_b32_e32 v99, 0
	global_load_dwordx4 v[84:87], v50, s[6:7]
	global_load_dwordx4 v[88:91], v50, s[6:7] offset:256
	v_add_u32_e32 v50, v50, v116
	v_cvt_pk_bf16_f32 v180, v92, v93
	v_cvt_pk_bf16_f32 v181, v94, v95
	v_cvt_pk_bf16_f32 v182, v96, v97
	v_cvt_pk_bf16_f32 v183, v98, v99
	global_store_dwordx2 v51, v[180:181], s[8:9]
	global_store_dwordx2 v51, v[182:183], s[8:9] offset:128
	v_add_u32_e32 v51, v51, v117
	s_waitcnt vmcnt(22)
	v_pk_fma_f32 v[172:173], v[108:109], v[92:93], v[0:1]
	v_pk_fma_f32 v[176:177], v[108:109], v[96:97], v[4:5]
	v_pk_fma_f32 v[174:175], v[110:111], v[94:95], v[2:3]
	v_pk_fma_f32 v[178:179], v[110:111], v[98:99], v[6:7]
	v_pk_fma_f32 v[100:101], v[112:113], v[96:97], v[172:173] neg_lo:[1,0,0] neg_hi:[1,0,0]
	v_pk_fma_f32 v[104:105], v[112:113], v[92:93], v[176:177]
	v_pk_fma_f32 v[102:103], v[114:115], v[98:99], v[174:175] neg_lo:[1,0,0] neg_hi:[1,0,0]
	v_pk_fma_f32 v[106:107], v[114:115], v[94:95], v[178:179]
	global_load_dwordx4 v[0:3], v50, s[6:7]
	global_load_dwordx4 v[4:7], v50, s[6:7] offset:256
	v_add_u32_e32 v50, v50, v116
	v_cvt_pk_bf16_f32 v184, v100, v101
	v_cvt_pk_bf16_f32 v185, v102, v103
	v_cvt_pk_bf16_f32 v186, v104, v105
	v_cvt_pk_bf16_f32 v187, v106, v107
	global_store_dwordx2 v51, v[184:185], s[8:9]
	global_store_dwordx2 v51, v[186:187], s[8:9] offset:128
	v_add_u32_e32 v51, v51, v117
	s_waitcnt vmcnt(24)
	v_pk_fma_f32 v[172:173], v[108:109], v[100:101], v[8:9]
	v_pk_fma_f32 v[176:177], v[108:109], v[104:105], v[12:13]
	v_pk_fma_f32 v[174:175], v[110:111], v[102:103], v[10:11]
	v_pk_fma_f32 v[178:179], v[110:111], v[106:107], v[14:15]
	v_pk_fma_f32 v[92:93], v[112:113], v[104:105], v[172:173] neg_lo:[1,0,0] neg_hi:[1,0,0]
	v_pk_fma_f32 v[96:97], v[112:113], v[100:101], v[176:177]
	v_pk_fma_f32 v[94:95], v[114:115], v[106:107], v[174:175] neg_lo:[1,0,0] neg_hi:[1,0,0]
	v_pk_fma_f32 v[98:99], v[114:115], v[102:103], v[178:179]
	global_load_dwordx4 v[8:11], v50, s[6:7]
	global_load_dwordx4 v[12:15], v50, s[6:7] offset:256
	v_add_u32_e32 v50, v50, v116
	v_cvt_pk_bf16_f32 v180, v92, v93
	v_cvt_pk_bf16_f32 v181, v94, v95
	v_cvt_pk_bf16_f32 v182, v96, v97
	v_cvt_pk_bf16_f32 v183, v98, v99
	global_store_dwordx2 v51, v[180:181], s[8:9]
	global_store_dwordx2 v51, v[182:183], s[8:9] offset:128
	v_add_u32_e32 v51, v51, v117
	s_waitcnt vmcnt(26)
	v_pk_fma_f32 v[172:173], v[108:109], v[92:93], v[16:17]
	v_pk_fma_f32 v[176:177], v[108:109], v[96:97], v[20:21]
	v_pk_fma_f32 v[174:175], v[110:111], v[94:95], v[18:19]
	v_pk_fma_f32 v[178:179], v[110:111], v[98:99], v[22:23]
	v_pk_fma_f32 v[100:101], v[112:113], v[96:97], v[172:173] neg_lo:[1,0,0] neg_hi:[1,0,0]
	v_pk_fma_f32 v[104:105], v[112:113], v[92:93], v[176:177]
	v_pk_fma_f32 v[102:103], v[114:115], v[98:99], v[174:175] neg_lo:[1,0,0] neg_hi:[1,0,0]
	v_pk_fma_f32 v[106:107], v[114:115], v[94:95], v[178:179]
	global_load_dwordx4 v[16:19], v50, s[6:7]
	global_load_dwordx4 v[20:23], v50, s[6:7] offset:256
	v_add_u32_e32 v50, v50, v116
	v_cvt_pk_bf16_f32 v184, v100, v101
	v_cvt_pk_bf16_f32 v185, v102, v103
	v_cvt_pk_bf16_f32 v186, v104, v105
	v_cvt_pk_bf16_f32 v187, v106, v107
	global_store_dwordx2 v51, v[184:185], s[8:9]
	global_store_dwordx2 v51, v[186:187], s[8:9] offset:128
	v_add_u32_e32 v51, v51, v117
	s_waitcnt vmcnt(28)
	v_pk_fma_f32 v[172:173], v[108:109], v[100:101], v[24:25]
	v_pk_fma_f32 v[176:177], v[108:109], v[104:105], v[28:29]
	v_pk_fma_f32 v[174:175], v[110:111], v[102:103], v[26:27]
	v_pk_fma_f32 v[178:179], v[110:111], v[106:107], v[30:31]
	v_pk_fma_f32 v[92:93], v[112:113], v[104:105], v[172:173] neg_lo:[1,0,0] neg_hi:[1,0,0]
	v_pk_fma_f32 v[96:97], v[112:113], v[100:101], v[176:177]
	v_pk_fma_f32 v[94:95], v[114:115], v[106:107], v[174:175] neg_lo:[1,0,0] neg_hi:[1,0,0]
	v_pk_fma_f32 v[98:99], v[114:115], v[102:103], v[178:179]
	global_load_dwordx4 v[24:27], v50, s[6:7]
	global_load_dwordx4 v[28:31], v50, s[6:7] offset:256
	v_add_u32_e32 v50, v50, v116
	v_cvt_pk_bf16_f32 v180, v92, v93
	v_cvt_pk_bf16_f32 v181, v94, v95
	v_cvt_pk_bf16_f32 v182, v96, v97
	v_cvt_pk_bf16_f32 v183, v98, v99
	global_store_dwordx2 v51, v[180:181], s[8:9]
	global_store_dwordx2 v51, v[182:183], s[8:9] offset:128
	v_add_u32_e32 v51, v51, v117
	s_waitcnt vmcnt(30)
	v_pk_fma_f32 v[172:173], v[108:109], v[92:93], v[32:33]
	v_pk_fma_f32 v[176:177], v[108:109], v[96:97], v[36:37]
	v_pk_fma_f32 v[174:175], v[110:111], v[94:95], v[34:35]
	v_pk_fma_f32 v[178:179], v[110:111], v[98:99], v[38:39]
	v_pk_fma_f32 v[100:101], v[112:113], v[96:97], v[172:173] neg_lo:[1,0,0] neg_hi:[1,0,0]
	v_pk_fma_f32 v[104:105], v[112:113], v[92:93], v[176:177]
	v_pk_fma_f32 v[102:103], v[114:115], v[98:99], v[174:175] neg_lo:[1,0,0] neg_hi:[1,0,0]
	v_pk_fma_f32 v[106:107], v[114:115], v[94:95], v[178:179]
	global_load_dwordx4 v[32:35], v50, s[6:7]
	global_load_dwordx4 v[36:39], v50, s[6:7] offset:256
	v_add_u32_e32 v50, v50, v116
	v_cvt_pk_bf16_f32 v184, v100, v101
	v_cvt_pk_bf16_f32 v185, v102, v103
	v_cvt_pk_bf16_f32 v186, v104, v105
	v_cvt_pk_bf16_f32 v187, v106, v107
	global_store_dwordx2 v51, v[184:185], s[8:9]
	global_store_dwordx2 v51, v[186:187], s[8:9] offset:128
	v_add_u32_e32 v51, v51, v117
	s_waitcnt vmcnt(32)
	v_pk_fma_f32 v[172:173], v[108:109], v[100:101], v[40:41]
	v_pk_fma_f32 v[176:177], v[108:109], v[104:105], v[44:45]
	v_pk_fma_f32 v[174:175], v[110:111], v[102:103], v[42:43]
	v_pk_fma_f32 v[178:179], v[110:111], v[106:107], v[46:47]
	v_pk_fma_f32 v[92:93], v[112:113], v[104:105], v[172:173] neg_lo:[1,0,0] neg_hi:[1,0,0]
	v_pk_fma_f32 v[96:97], v[112:113], v[100:101], v[176:177]
	v_pk_fma_f32 v[94:95], v[114:115], v[106:107], v[174:175] neg_lo:[1,0,0] neg_hi:[1,0,0]
	v_pk_fma_f32 v[98:99], v[114:115], v[102:103], v[178:179]
	global_load_dwordx4 v[40:43], v50, s[6:7]
	global_load_dwordx4 v[44:47], v50, s[6:7] offset:256
	v_add_u32_e32 v50, v50, v116
	v_cvt_pk_bf16_f32 v180, v92, v93
	v_cvt_pk_bf16_f32 v181, v94, v95
	v_cvt_pk_bf16_f32 v182, v96, v97
	v_cvt_pk_bf16_f32 v183, v98, v99
	global_store_dwordx2 v51, v[180:181], s[8:9]
	global_store_dwordx2 v51, v[182:183], s[8:9] offset:128
	v_add_u32_e32 v51, v51, v117
	s_waitcnt vmcnt(34)
	v_pk_fma_f32 v[172:173], v[108:109], v[92:93], v[52:53]
	v_pk_fma_f32 v[176:177], v[108:109], v[96:97], v[56:57]
	v_pk_fma_f32 v[174:175], v[110:111], v[94:95], v[54:55]
	v_pk_fma_f32 v[178:179], v[110:111], v[98:99], v[58:59]
	v_pk_fma_f32 v[100:101], v[112:113], v[96:97], v[172:173] neg_lo:[1,0,0] neg_hi:[1,0,0]
	v_pk_fma_f32 v[104:105], v[112:113], v[92:93], v[176:177]
	v_pk_fma_f32 v[102:103], v[114:115], v[98:99], v[174:175] neg_lo:[1,0,0] neg_hi:[1,0,0]
	v_pk_fma_f32 v[106:107], v[114:115], v[94:95], v[178:179]
	global_load_dwordx4 v[52:55], v50, s[6:7]
	global_load_dwordx4 v[56:59], v50, s[6:7] offset:256
	v_add_u32_e32 v50, v50, v116
	v_cvt_pk_bf16_f32 v184, v100, v101
	v_cvt_pk_bf16_f32 v185, v102, v103
	v_cvt_pk_bf16_f32 v186, v104, v105
	v_cvt_pk_bf16_f32 v187, v106, v107
	global_store_dwordx2 v51, v[184:185], s[8:9]
	global_store_dwordx2 v51, v[186:187], s[8:9] offset:128
	v_add_u32_e32 v51, v51, v117
	s_waitcnt vmcnt(36)
	v_pk_fma_f32 v[172:173], v[108:109], v[100:101], v[60:61]
	v_pk_fma_f32 v[176:177], v[108:109], v[104:105], v[64:65]
	v_pk_fma_f32 v[174:175], v[110:111], v[102:103], v[62:63]
	v_pk_fma_f32 v[178:179], v[110:111], v[106:107], v[66:67]
	v_pk_fma_f32 v[92:93], v[112:113], v[104:105], v[172:173] neg_lo:[1,0,0] neg_hi:[1,0,0]
	v_pk_fma_f32 v[96:97], v[112:113], v[100:101], v[176:177]
	v_pk_fma_f32 v[94:95], v[114:115], v[106:107], v[174:175] neg_lo:[1,0,0] neg_hi:[1,0,0]
	v_pk_fma_f32 v[98:99], v[114:115], v[102:103], v[178:179]
	global_load_dwordx4 v[60:63], v50, s[6:7]
	global_load_dwordx4 v[64:67], v50, s[6:7] offset:256
	v_add_u32_e32 v50, v50, v116
	v_cvt_pk_bf16_f32 v180, v92, v93
	v_cvt_pk_bf16_f32 v181, v94, v95
	v_cvt_pk_bf16_f32 v182, v96, v97
	v_cvt_pk_bf16_f32 v183, v98, v99
	v_add_u32_e32 v51, v51, v162
	global_store_dwordx2 v51, v[180:181], s[8:9]
	global_store_dwordx2 v51, v[182:183], s[8:9] offset:128
	v_add_u32_e32 v51, v51, v117
	s_waitcnt vmcnt(38)
	v_pk_fma_f32 v[172:173], v[108:109], v[92:93], v[68:69]
	v_pk_fma_f32 v[176:177], v[108:109], v[96:97], v[72:73]
	v_pk_fma_f32 v[174:175], v[110:111], v[94:95], v[70:71]
	v_pk_fma_f32 v[178:179], v[110:111], v[98:99], v[74:75]
	v_pk_fma_f32 v[100:101], v[112:113], v[96:97], v[172:173] neg_lo:[1,0,0] neg_hi:[1,0,0]
	v_pk_fma_f32 v[104:105], v[112:113], v[92:93], v[176:177]
	v_pk_fma_f32 v[102:103], v[114:115], v[98:99], v[174:175] neg_lo:[1,0,0] neg_hi:[1,0,0]
	v_pk_fma_f32 v[106:107], v[114:115], v[94:95], v[178:179]
	global_load_dwordx4 v[68:71], v50, s[6:7]
	global_load_dwordx4 v[72:75], v50, s[6:7] offset:256
	v_add_u32_e32 v50, v50, v116
	v_cvt_pk_bf16_f32 v184, v100, v101
	v_cvt_pk_bf16_f32 v185, v102, v103
	v_cvt_pk_bf16_f32 v186, v104, v105
	v_cvt_pk_bf16_f32 v187, v106, v107
	global_store_dwordx2 v51, v[184:185], s[8:9]
	global_store_dwordx2 v51, v[186:187], s[8:9] offset:128
	v_add_u32_e32 v51, v51, v117
	s_waitcnt vmcnt(40)
	v_pk_fma_f32 v[172:173], v[108:109], v[100:101], v[76:77]
	v_pk_fma_f32 v[176:177], v[108:109], v[104:105], v[80:81]
	v_pk_fma_f32 v[174:175], v[110:111], v[102:103], v[78:79]
	v_pk_fma_f32 v[178:179], v[110:111], v[106:107], v[82:83]
	v_pk_fma_f32 v[92:93], v[112:113], v[104:105], v[172:173] neg_lo:[1,0,0] neg_hi:[1,0,0]
	v_pk_fma_f32 v[96:97], v[112:113], v[100:101], v[176:177]
	v_pk_fma_f32 v[94:95], v[114:115], v[106:107], v[174:175] neg_lo:[1,0,0] neg_hi:[1,0,0]
	v_pk_fma_f32 v[98:99], v[114:115], v[102:103], v[178:179]
	global_load_dwordx4 v[76:79], v50, s[6:7]
	global_load_dwordx4 v[80:83], v50, s[6:7] offset:256
	v_add_u32_e32 v50, v50, v116
	v_cvt_pk_bf16_f32 v180, v92, v93
	v_cvt_pk_bf16_f32 v181, v94, v95
	v_cvt_pk_bf16_f32 v182, v96, v97
	v_cvt_pk_bf16_f32 v183, v98, v99
	global_store_dwordx2 v51, v[180:181], s[8:9]
	global_store_dwordx2 v51, v[182:183], s[8:9] offset:128
	v_add_u32_e32 v51, v51, v117
	s_waitcnt vmcnt(42)
	v_pk_fma_f32 v[172:173], v[108:109], v[92:93], v[84:85]
	v_pk_fma_f32 v[176:177], v[108:109], v[96:97], v[88:89]
	v_pk_fma_f32 v[174:175], v[110:111], v[94:95], v[86:87]
	v_pk_fma_f32 v[178:179], v[110:111], v[98:99], v[90:91]
	v_pk_fma_f32 v[100:101], v[112:113], v[96:97], v[172:173] neg_lo:[1,0,0] neg_hi:[1,0,0]
	v_pk_fma_f32 v[104:105], v[112:113], v[92:93], v[176:177]
	v_pk_fma_f32 v[102:103], v[114:115], v[98:99], v[174:175] neg_lo:[1,0,0] neg_hi:[1,0,0]
	v_pk_fma_f32 v[106:107], v[114:115], v[94:95], v[178:179]
	global_load_dwordx4 v[84:87], v50, s[6:7]
	global_load_dwordx4 v[88:91], v50, s[6:7] offset:256
	v_add_u32_e32 v50, v50, v116
	v_cvt_pk_bf16_f32 v184, v100, v101
	v_cvt_pk_bf16_f32 v185, v102, v103
	v_cvt_pk_bf16_f32 v186, v104, v105
	v_cvt_pk_bf16_f32 v187, v106, v107
	global_store_dwordx2 v51, v[184:185], s[8:9]
	global_store_dwordx2 v51, v[186:187], s[8:9] offset:128
	v_add_u32_e32 v51, v51, v117
	s_waitcnt vmcnt(42)
	v_pk_fma_f32 v[172:173], v[108:109], v[100:101], v[0:1]
	v_pk_fma_f32 v[176:177], v[108:109], v[104:105], v[4:5]
	v_pk_fma_f32 v[174:175], v[110:111], v[102:103], v[2:3]
	v_pk_fma_f32 v[178:179], v[110:111], v[106:107], v[6:7]
	v_pk_fma_f32 v[92:93], v[112:113], v[104:105], v[172:173] neg_lo:[1,0,0] neg_hi:[1,0,0]
	v_pk_fma_f32 v[96:97], v[112:113], v[100:101], v[176:177]
	v_pk_fma_f32 v[94:95], v[114:115], v[106:107], v[174:175] neg_lo:[1,0,0] neg_hi:[1,0,0]
	v_pk_fma_f32 v[98:99], v[114:115], v[102:103], v[178:179]
	global_load_dwordx4 v[0:3], v50, s[6:7]
	global_load_dwordx4 v[4:7], v50, s[6:7] offset:256
	v_add_u32_e32 v50, v50, v116
	v_cvt_pk_bf16_f32 v180, v92, v93
	v_cvt_pk_bf16_f32 v181, v94, v95
	v_cvt_pk_bf16_f32 v182, v96, v97
	v_cvt_pk_bf16_f32 v183, v98, v99
	global_store_dwordx2 v51, v[180:181], s[8:9]
	global_store_dwordx2 v51, v[182:183], s[8:9] offset:128
	v_add_u32_e32 v51, v51, v117
	s_waitcnt vmcnt(42)
	v_pk_fma_f32 v[172:173], v[108:109], v[92:93], v[8:9]
	v_pk_fma_f32 v[176:177], v[108:109], v[96:97], v[12:13]
	v_pk_fma_f32 v[174:175], v[110:111], v[94:95], v[10:11]
	v_pk_fma_f32 v[178:179], v[110:111], v[98:99], v[14:15]
	v_pk_fma_f32 v[100:101], v[112:113], v[96:97], v[172:173] neg_lo:[1,0,0] neg_hi:[1,0,0]
	v_pk_fma_f32 v[104:105], v[112:113], v[92:93], v[176:177]
	v_pk_fma_f32 v[102:103], v[114:115], v[98:99], v[174:175] neg_lo:[1,0,0] neg_hi:[1,0,0]
	v_pk_fma_f32 v[106:107], v[114:115], v[94:95], v[178:179]
	global_load_dwordx4 v[8:11], v50, s[6:7]
	global_load_dwordx4 v[12:15], v50, s[6:7] offset:256
	v_add_u32_e32 v50, v50, v116
	v_cvt_pk_bf16_f32 v184, v100, v101
	v_cvt_pk_bf16_f32 v185, v102, v103
	v_cvt_pk_bf16_f32 v186, v104, v105
	v_cvt_pk_bf16_f32 v187, v106, v107
	global_store_dwordx2 v51, v[184:185], s[8:9]
	global_store_dwordx2 v51, v[186:187], s[8:9] offset:128
	v_add_u32_e32 v51, v51, v117
	s_waitcnt vmcnt(42)
	v_pk_fma_f32 v[172:173], v[108:109], v[100:101], v[16:17]
	v_pk_fma_f32 v[176:177], v[108:109], v[104:105], v[20:21]
	v_pk_fma_f32 v[174:175], v[110:111], v[102:103], v[18:19]
	v_pk_fma_f32 v[178:179], v[110:111], v[106:107], v[22:23]
	v_pk_fma_f32 v[92:93], v[112:113], v[104:105], v[172:173] neg_lo:[1,0,0] neg_hi:[1,0,0]
	v_pk_fma_f32 v[96:97], v[112:113], v[100:101], v[176:177]
	v_pk_fma_f32 v[94:95], v[114:115], v[106:107], v[174:175] neg_lo:[1,0,0] neg_hi:[1,0,0]
	v_pk_fma_f32 v[98:99], v[114:115], v[102:103], v[178:179]
	global_load_dwordx4 v[16:19], v50, s[6:7]
	global_load_dwordx4 v[20:23], v50, s[6:7] offset:256
	v_add_u32_e32 v50, v50, v116
	v_cvt_pk_bf16_f32 v180, v92, v93
	v_cvt_pk_bf16_f32 v181, v94, v95
	v_cvt_pk_bf16_f32 v182, v96, v97
	v_cvt_pk_bf16_f32 v183, v98, v99
	global_store_dwordx2 v51, v[180:181], s[8:9]
	global_store_dwordx2 v51, v[182:183], s[8:9] offset:128
	v_add_u32_e32 v51, v51, v117
	s_waitcnt vmcnt(42)
	v_pk_fma_f32 v[172:173], v[108:109], v[92:93], v[24:25]
	v_pk_fma_f32 v[176:177], v[108:109], v[96:97], v[28:29]
	v_pk_fma_f32 v[174:175], v[110:111], v[94:95], v[26:27]
	v_pk_fma_f32 v[178:179], v[110:111], v[98:99], v[30:31]
	v_pk_fma_f32 v[100:101], v[112:113], v[96:97], v[172:173] neg_lo:[1,0,0] neg_hi:[1,0,0]
	v_pk_fma_f32 v[104:105], v[112:113], v[92:93], v[176:177]
	v_pk_fma_f32 v[102:103], v[114:115], v[98:99], v[174:175] neg_lo:[1,0,0] neg_hi:[1,0,0]
	v_pk_fma_f32 v[106:107], v[114:115], v[94:95], v[178:179]
	global_load_dwordx4 v[24:27], v50, s[6:7]
	global_load_dwordx4 v[28:31], v50, s[6:7] offset:256
	v_add_u32_e32 v50, v50, v116
	v_cvt_pk_bf16_f32 v184, v100, v101
	v_cvt_pk_bf16_f32 v185, v102, v103
	v_cvt_pk_bf16_f32 v186, v104, v105
	v_cvt_pk_bf16_f32 v187, v106, v107
	global_store_dwordx2 v51, v[184:185], s[8:9]
	global_store_dwordx2 v51, v[186:187], s[8:9] offset:128
	v_add_u32_e32 v51, v51, v117
	s_waitcnt vmcnt(42)
	v_pk_fma_f32 v[172:173], v[108:109], v[100:101], v[32:33]
	v_pk_fma_f32 v[176:177], v[108:109], v[104:105], v[36:37]
	v_pk_fma_f32 v[174:175], v[110:111], v[102:103], v[34:35]
	v_pk_fma_f32 v[178:179], v[110:111], v[106:107], v[38:39]
	v_pk_fma_f32 v[92:93], v[112:113], v[104:105], v[172:173] neg_lo:[1,0,0] neg_hi:[1,0,0]
	v_pk_fma_f32 v[96:97], v[112:113], v[100:101], v[176:177]
	v_pk_fma_f32 v[94:95], v[114:115], v[106:107], v[174:175] neg_lo:[1,0,0] neg_hi:[1,0,0]
	v_pk_fma_f32 v[98:99], v[114:115], v[102:103], v[178:179]
	global_load_dwordx4 v[32:35], v50, s[6:7]
	global_load_dwordx4 v[36:39], v50, s[6:7] offset:256
	v_add_u32_e32 v50, v50, v116
	v_cvt_pk_bf16_f32 v180, v92, v93
	v_cvt_pk_bf16_f32 v181, v94, v95
	v_cvt_pk_bf16_f32 v182, v96, v97
	v_cvt_pk_bf16_f32 v183, v98, v99
	global_store_dwordx2 v51, v[180:181], s[8:9]
	global_store_dwordx2 v51, v[182:183], s[8:9] offset:128
	v_add_u32_e32 v51, v51, v117
	s_waitcnt vmcnt(42)
	v_pk_fma_f32 v[172:173], v[108:109], v[92:93], v[40:41]
	v_pk_fma_f32 v[176:177], v[108:109], v[96:97], v[44:45]
	v_pk_fma_f32 v[174:175], v[110:111], v[94:95], v[42:43]
	v_pk_fma_f32 v[178:179], v[110:111], v[98:99], v[46:47]
	v_pk_fma_f32 v[100:101], v[112:113], v[96:97], v[172:173] neg_lo:[1,0,0] neg_hi:[1,0,0]
	v_pk_fma_f32 v[104:105], v[112:113], v[92:93], v[176:177]
	v_pk_fma_f32 v[102:103], v[114:115], v[98:99], v[174:175] neg_lo:[1,0,0] neg_hi:[1,0,0]
	v_pk_fma_f32 v[106:107], v[114:115], v[94:95], v[178:179]
	global_load_dwordx4 v[40:43], v50, s[6:7]
	global_load_dwordx4 v[44:47], v50, s[6:7] offset:256
	v_add_u32_e32 v50, v50, v116
	v_cvt_pk_bf16_f32 v184, v100, v101
	v_cvt_pk_bf16_f32 v185, v102, v103
	v_cvt_pk_bf16_f32 v186, v104, v105
	v_cvt_pk_bf16_f32 v187, v106, v107
	global_store_dwordx2 v51, v[184:185], s[8:9]
	global_store_dwordx2 v51, v[186:187], s[8:9] offset:128
	v_add_u32_e32 v51, v51, v117
	s_waitcnt vmcnt(42)
	v_pk_fma_f32 v[172:173], v[108:109], v[100:101], v[52:53]
	v_pk_fma_f32 v[176:177], v[108:109], v[104:105], v[56:57]
	v_pk_fma_f32 v[174:175], v[110:111], v[102:103], v[54:55]
	v_pk_fma_f32 v[178:179], v[110:111], v[106:107], v[58:59]
	v_pk_fma_f32 v[92:93], v[112:113], v[104:105], v[172:173] neg_lo:[1,0,0] neg_hi:[1,0,0]
	v_pk_fma_f32 v[96:97], v[112:113], v[100:101], v[176:177]
	v_pk_fma_f32 v[94:95], v[114:115], v[106:107], v[174:175] neg_lo:[1,0,0] neg_hi:[1,0,0]
	v_pk_fma_f32 v[98:99], v[114:115], v[102:103], v[178:179]
	global_load_dwordx4 v[52:55], v50, s[6:7]
	global_load_dwordx4 v[56:59], v50, s[6:7] offset:256
	v_add_u32_e32 v50, v50, v116
	v_cvt_pk_bf16_f32 v180, v92, v93
	v_cvt_pk_bf16_f32 v181, v94, v95
	v_cvt_pk_bf16_f32 v182, v96, v97
	v_cvt_pk_bf16_f32 v183, v98, v99
	global_store_dwordx2 v51, v[180:181], s[8:9]
	global_store_dwordx2 v51, v[182:183], s[8:9] offset:128
	v_add_u32_e32 v51, v51, v117
	s_waitcnt vmcnt(42)
	v_pk_fma_f32 v[172:173], v[108:109], v[92:93], v[60:61]
	v_pk_fma_f32 v[176:177], v[108:109], v[96:97], v[64:65]
	v_pk_fma_f32 v[174:175], v[110:111], v[94:95], v[62:63]
	v_pk_fma_f32 v[178:179], v[110:111], v[98:99], v[66:67]
	v_pk_fma_f32 v[100:101], v[112:113], v[96:97], v[172:173] neg_lo:[1,0,0] neg_hi:[1,0,0]
	v_pk_fma_f32 v[104:105], v[112:113], v[92:93], v[176:177]
	v_pk_fma_f32 v[102:103], v[114:115], v[98:99], v[174:175] neg_lo:[1,0,0] neg_hi:[1,0,0]
	v_pk_fma_f32 v[106:107], v[114:115], v[94:95], v[178:179]
	global_load_dwordx4 v[60:63], v50, s[6:7]
	global_load_dwordx4 v[64:67], v50, s[6:7] offset:256
	v_add_u32_e32 v50, v50, v116
	v_cvt_pk_bf16_f32 v184, v100, v101
	v_cvt_pk_bf16_f32 v185, v102, v103
	v_cvt_pk_bf16_f32 v186, v104, v105
	v_cvt_pk_bf16_f32 v187, v106, v107
	global_store_dwordx2 v51, v[184:185], s[8:9]
	global_store_dwordx2 v51, v[186:187], s[8:9] offset:128
	v_add_u32_e32 v51, v51, v117
	s_waitcnt vmcnt(42)
	v_pk_fma_f32 v[172:173], v[108:109], v[100:101], v[68:69]
	v_pk_fma_f32 v[176:177], v[108:109], v[104:105], v[72:73]
	v_pk_fma_f32 v[174:175], v[110:111], v[102:103], v[70:71]
	v_pk_fma_f32 v[178:179], v[110:111], v[106:107], v[74:75]
	v_pk_fma_f32 v[92:93], v[112:113], v[104:105], v[172:173] neg_lo:[1,0,0] neg_hi:[1,0,0]
	v_pk_fma_f32 v[96:97], v[112:113], v[100:101], v[176:177]
	v_pk_fma_f32 v[94:95], v[114:115], v[106:107], v[174:175] neg_lo:[1,0,0] neg_hi:[1,0,0]
	v_pk_fma_f32 v[98:99], v[114:115], v[102:103], v[178:179]
	global_load_dwordx4 v[68:71], v50, s[6:7]
	global_load_dwordx4 v[72:75], v50, s[6:7] offset:256
	v_add_u32_e32 v50, v50, v116
	v_cvt_pk_bf16_f32 v180, v92, v93
	v_cvt_pk_bf16_f32 v181, v94, v95
	v_cvt_pk_bf16_f32 v182, v96, v97
	v_cvt_pk_bf16_f32 v183, v98, v99
	global_store_dwordx2 v51, v[180:181], s[8:9]
	global_store_dwordx2 v51, v[182:183], s[8:9] offset:128
	v_add_u32_e32 v51, v51, v117
	s_waitcnt vmcnt(42)
	v_pk_fma_f32 v[172:173], v[108:109], v[92:93], v[76:77]
	v_pk_fma_f32 v[176:177], v[108:109], v[96:97], v[80:81]
	v_pk_fma_f32 v[174:175], v[110:111], v[94:95], v[78:79]
	v_pk_fma_f32 v[178:179], v[110:111], v[98:99], v[82:83]
	v_pk_fma_f32 v[100:101], v[112:113], v[96:97], v[172:173] neg_lo:[1,0,0] neg_hi:[1,0,0]
	v_pk_fma_f32 v[104:105], v[112:113], v[92:93], v[176:177]
	v_pk_fma_f32 v[102:103], v[114:115], v[98:99], v[174:175] neg_lo:[1,0,0] neg_hi:[1,0,0]
	v_pk_fma_f32 v[106:107], v[114:115], v[94:95], v[178:179]
	global_load_dwordx4 v[76:79], v50, s[6:7]
	global_load_dwordx4 v[80:83], v50, s[6:7] offset:256
	v_add_u32_e32 v50, v50, v116
	v_cvt_pk_bf16_f32 v184, v100, v101
	v_cvt_pk_bf16_f32 v185, v102, v103
	v_cvt_pk_bf16_f32 v186, v104, v105
	v_cvt_pk_bf16_f32 v187, v106, v107
	global_store_dwordx2 v51, v[184:185], s[8:9]
	global_store_dwordx2 v51, v[186:187], s[8:9] offset:128
	v_add_u32_e32 v51, v51, v117
	s_waitcnt vmcnt(42)
	v_pk_fma_f32 v[172:173], v[108:109], v[100:101], v[84:85]
	v_pk_fma_f32 v[176:177], v[108:109], v[104:105], v[88:89]
	v_pk_fma_f32 v[174:175], v[110:111], v[102:103], v[86:87]
	v_pk_fma_f32 v[178:179], v[110:111], v[106:107], v[90:91]
	v_pk_fma_f32 v[92:93], v[112:113], v[104:105], v[172:173] neg_lo:[1,0,0] neg_hi:[1,0,0]
	v_pk_fma_f32 v[96:97], v[112:113], v[100:101], v[176:177]
	v_pk_fma_f32 v[94:95], v[114:115], v[106:107], v[174:175] neg_lo:[1,0,0] neg_hi:[1,0,0]
	v_pk_fma_f32 v[98:99], v[114:115], v[102:103], v[178:179]
	global_load_dwordx4 v[84:87], v50, s[6:7]
	global_load_dwordx4 v[88:91], v50, s[6:7] offset:256
	v_add_u32_e32 v50, v50, v116
	v_cvt_pk_bf16_f32 v180, v92, v93
	v_cvt_pk_bf16_f32 v181, v94, v95
	v_cvt_pk_bf16_f32 v182, v96, v97
	v_cvt_pk_bf16_f32 v183, v98, v99
	global_store_dwordx2 v51, v[180:181], s[8:9]
	global_store_dwordx2 v51, v[182:183], s[8:9] offset:128
	v_add_u32_e32 v51, v51, v117
	s_waitcnt vmcnt(42)
	v_pk_fma_f32 v[172:173], v[108:109], v[92:93], v[0:1]
	v_pk_fma_f32 v[176:177], v[108:109], v[96:97], v[4:5]
	v_pk_fma_f32 v[174:175], v[110:111], v[94:95], v[2:3]
	v_pk_fma_f32 v[178:179], v[110:111], v[98:99], v[6:7]
	v_pk_fma_f32 v[100:101], v[112:113], v[96:97], v[172:173] neg_lo:[1,0,0] neg_hi:[1,0,0]
	v_pk_fma_f32 v[104:105], v[112:113], v[92:93], v[176:177]
	v_pk_fma_f32 v[102:103], v[114:115], v[98:99], v[174:175] neg_lo:[1,0,0] neg_hi:[1,0,0]
	v_pk_fma_f32 v[106:107], v[114:115], v[94:95], v[178:179]
	global_load_dwordx4 v[0:3], v50, s[6:7]
	global_load_dwordx4 v[4:7], v50, s[6:7] offset:256
	v_add_u32_e32 v50, v50, v116
	v_cvt_pk_bf16_f32 v184, v100, v101
	v_cvt_pk_bf16_f32 v185, v102, v103
	v_cvt_pk_bf16_f32 v186, v104, v105
	v_cvt_pk_bf16_f32 v187, v106, v107
	global_store_dwordx2 v51, v[184:185], s[8:9]
	global_store_dwordx2 v51, v[186:187], s[8:9] offset:128
	v_add_u32_e32 v51, v51, v117
	s_waitcnt vmcnt(42)
	v_pk_fma_f32 v[172:173], v[108:109], v[100:101], v[8:9]
	v_pk_fma_f32 v[176:177], v[108:109], v[104:105], v[12:13]
	v_pk_fma_f32 v[174:175], v[110:111], v[102:103], v[10:11]
	v_pk_fma_f32 v[178:179], v[110:111], v[106:107], v[14:15]
	v_pk_fma_f32 v[92:93], v[112:113], v[104:105], v[172:173] neg_lo:[1,0,0] neg_hi:[1,0,0]
	v_pk_fma_f32 v[96:97], v[112:113], v[100:101], v[176:177]
	v_pk_fma_f32 v[94:95], v[114:115], v[106:107], v[174:175] neg_lo:[1,0,0] neg_hi:[1,0,0]
	v_pk_fma_f32 v[98:99], v[114:115], v[102:103], v[178:179]
	global_load_dwordx4 v[8:11], v50, s[6:7]
	global_load_dwordx4 v[12:15], v50, s[6:7] offset:256
	v_add_u32_e32 v50, v50, v116
	v_cvt_pk_bf16_f32 v180, v92, v93
	v_cvt_pk_bf16_f32 v181, v94, v95
	v_cvt_pk_bf16_f32 v182, v96, v97
	v_cvt_pk_bf16_f32 v183, v98, v99
	global_store_dwordx2 v51, v[180:181], s[8:9]
	global_store_dwordx2 v51, v[182:183], s[8:9] offset:128
	v_add_u32_e32 v51, v51, v117
	s_waitcnt vmcnt(42)
	v_pk_fma_f32 v[172:173], v[108:109], v[92:93], v[16:17]
	v_pk_fma_f32 v[176:177], v[108:109], v[96:97], v[20:21]
	v_pk_fma_f32 v[174:175], v[110:111], v[94:95], v[18:19]
	v_pk_fma_f32 v[178:179], v[110:111], v[98:99], v[22:23]
	v_pk_fma_f32 v[100:101], v[112:113], v[96:97], v[172:173] neg_lo:[1,0,0] neg_hi:[1,0,0]
	v_pk_fma_f32 v[104:105], v[112:113], v[92:93], v[176:177]
	v_pk_fma_f32 v[102:103], v[114:115], v[98:99], v[174:175] neg_lo:[1,0,0] neg_hi:[1,0,0]
	v_pk_fma_f32 v[106:107], v[114:115], v[94:95], v[178:179]
	global_load_dwordx4 v[16:19], v50, s[6:7]
	global_load_dwordx4 v[20:23], v50, s[6:7] offset:256
	v_add_u32_e32 v50, v50, v116
	v_cvt_pk_bf16_f32 v184, v100, v101
	v_cvt_pk_bf16_f32 v185, v102, v103
	v_cvt_pk_bf16_f32 v186, v104, v105
	v_cvt_pk_bf16_f32 v187, v106, v107
	global_store_dwordx2 v51, v[184:185], s[8:9]
	global_store_dwordx2 v51, v[186:187], s[8:9] offset:128
	v_add_u32_e32 v51, v51, v117
	s_waitcnt vmcnt(42)
	v_pk_fma_f32 v[172:173], v[108:109], v[100:101], v[24:25]
	v_pk_fma_f32 v[176:177], v[108:109], v[104:105], v[28:29]
	v_pk_fma_f32 v[174:175], v[110:111], v[102:103], v[26:27]
	v_pk_fma_f32 v[178:179], v[110:111], v[106:107], v[30:31]
	v_pk_fma_f32 v[92:93], v[112:113], v[104:105], v[172:173] neg_lo:[1,0,0] neg_hi:[1,0,0]
	v_pk_fma_f32 v[96:97], v[112:113], v[100:101], v[176:177]
	v_pk_fma_f32 v[94:95], v[114:115], v[106:107], v[174:175] neg_lo:[1,0,0] neg_hi:[1,0,0]
	v_pk_fma_f32 v[98:99], v[114:115], v[102:103], v[178:179]
	global_load_dwordx4 v[24:27], v50, s[6:7]
	global_load_dwordx4 v[28:31], v50, s[6:7] offset:256
	v_add_u32_e32 v50, v50, v116
	v_cvt_pk_bf16_f32 v180, v92, v93
	v_cvt_pk_bf16_f32 v181, v94, v95
	v_cvt_pk_bf16_f32 v182, v96, v97
	v_cvt_pk_bf16_f32 v183, v98, v99
	global_store_dwordx2 v51, v[180:181], s[8:9]
	global_store_dwordx2 v51, v[182:183], s[8:9] offset:128
	v_add_u32_e32 v51, v51, v117
	s_waitcnt vmcnt(42)
	v_pk_fma_f32 v[172:173], v[108:109], v[92:93], v[32:33]
	v_pk_fma_f32 v[176:177], v[108:109], v[96:97], v[36:37]
	v_pk_fma_f32 v[174:175], v[110:111], v[94:95], v[34:35]
	v_pk_fma_f32 v[178:179], v[110:111], v[98:99], v[38:39]
	v_pk_fma_f32 v[100:101], v[112:113], v[96:97], v[172:173] neg_lo:[1,0,0] neg_hi:[1,0,0]
	v_pk_fma_f32 v[104:105], v[112:113], v[92:93], v[176:177]
	v_pk_fma_f32 v[102:103], v[114:115], v[98:99], v[174:175] neg_lo:[1,0,0] neg_hi:[1,0,0]
	v_pk_fma_f32 v[106:107], v[114:115], v[94:95], v[178:179]
	global_load_dwordx4 v[32:35], v50, s[6:7]
	global_load_dwordx4 v[36:39], v50, s[6:7] offset:256
	v_add_u32_e32 v50, v50, v116
	v_cvt_pk_bf16_f32 v184, v100, v101
	v_cvt_pk_bf16_f32 v185, v102, v103
	v_cvt_pk_bf16_f32 v186, v104, v105
	v_cvt_pk_bf16_f32 v187, v106, v107
	global_store_dwordx2 v51, v[184:185], s[8:9]
	global_store_dwordx2 v51, v[186:187], s[8:9] offset:128
	v_add_u32_e32 v51, v51, v117
	s_waitcnt vmcnt(42)
	v_pk_fma_f32 v[172:173], v[108:109], v[100:101], v[40:41]
	v_pk_fma_f32 v[176:177], v[108:109], v[104:105], v[44:45]
	v_pk_fma_f32 v[174:175], v[110:111], v[102:103], v[42:43]
	v_pk_fma_f32 v[178:179], v[110:111], v[106:107], v[46:47]
	v_pk_fma_f32 v[92:93], v[112:113], v[104:105], v[172:173] neg_lo:[1,0,0] neg_hi:[1,0,0]
	v_pk_fma_f32 v[96:97], v[112:113], v[100:101], v[176:177]
	v_pk_fma_f32 v[94:95], v[114:115], v[106:107], v[174:175] neg_lo:[1,0,0] neg_hi:[1,0,0]
	v_pk_fma_f32 v[98:99], v[114:115], v[102:103], v[178:179]
	global_load_dwordx4 v[40:43], v50, s[6:7]
	global_load_dwordx4 v[44:47], v50, s[6:7] offset:256
	v_add_u32_e32 v50, v50, v116
	v_cvt_pk_bf16_f32 v180, v92, v93
	v_cvt_pk_bf16_f32 v181, v94, v95
	v_cvt_pk_bf16_f32 v182, v96, v97
	v_cvt_pk_bf16_f32 v183, v98, v99
	global_store_dwordx2 v51, v[180:181], s[8:9]
	global_store_dwordx2 v51, v[182:183], s[8:9] offset:128
	v_add_u32_e32 v51, v51, v117
	s_waitcnt vmcnt(42)
	v_pk_fma_f32 v[172:173], v[108:109], v[92:93], v[52:53]
	v_pk_fma_f32 v[176:177], v[108:109], v[96:97], v[56:57]
	v_pk_fma_f32 v[174:175], v[110:111], v[94:95], v[54:55]
	v_pk_fma_f32 v[178:179], v[110:111], v[98:99], v[58:59]
	v_pk_fma_f32 v[100:101], v[112:113], v[96:97], v[172:173] neg_lo:[1,0,0] neg_hi:[1,0,0]
	v_pk_fma_f32 v[104:105], v[112:113], v[92:93], v[176:177]
	v_pk_fma_f32 v[102:103], v[114:115], v[98:99], v[174:175] neg_lo:[1,0,0] neg_hi:[1,0,0]
	v_pk_fma_f32 v[106:107], v[114:115], v[94:95], v[178:179]
	global_load_dwordx4 v[52:55], v50, s[6:7]
	global_load_dwordx4 v[56:59], v50, s[6:7] offset:256
	v_add_u32_e32 v50, v50, v116
	v_cvt_pk_bf16_f32 v184, v100, v101
	v_cvt_pk_bf16_f32 v185, v102, v103
	v_cvt_pk_bf16_f32 v186, v104, v105
	v_cvt_pk_bf16_f32 v187, v106, v107
	global_store_dwordx2 v51, v[184:185], s[8:9]
	global_store_dwordx2 v51, v[186:187], s[8:9] offset:128
	v_add_u32_e32 v51, v51, v117
	s_waitcnt vmcnt(42)
	v_pk_fma_f32 v[172:173], v[108:109], v[100:101], v[60:61]
	v_pk_fma_f32 v[176:177], v[108:109], v[104:105], v[64:65]
	v_pk_fma_f32 v[174:175], v[110:111], v[102:103], v[62:63]
	v_pk_fma_f32 v[178:179], v[110:111], v[106:107], v[66:67]
	v_pk_fma_f32 v[92:93], v[112:113], v[104:105], v[172:173] neg_lo:[1,0,0] neg_hi:[1,0,0]
	v_pk_fma_f32 v[96:97], v[112:113], v[100:101], v[176:177]
	v_pk_fma_f32 v[94:95], v[114:115], v[106:107], v[174:175] neg_lo:[1,0,0] neg_hi:[1,0,0]
	v_pk_fma_f32 v[98:99], v[114:115], v[102:103], v[178:179]
	global_load_dwordx4 v[60:63], v50, s[6:7]
	global_load_dwordx4 v[64:67], v50, s[6:7] offset:256
	v_add_u32_e32 v50, v50, v116
	v_cvt_pk_bf16_f32 v180, v92, v93
	v_cvt_pk_bf16_f32 v181, v94, v95
	v_cvt_pk_bf16_f32 v182, v96, v97
	v_cvt_pk_bf16_f32 v183, v98, v99
	global_store_dwordx2 v51, v[180:181], s[8:9]
	global_store_dwordx2 v51, v[182:183], s[8:9] offset:128
	v_add_u32_e32 v51, v51, v117
	s_waitcnt vmcnt(42)
	v_pk_fma_f32 v[172:173], v[108:109], v[92:93], v[68:69]
	v_pk_fma_f32 v[176:177], v[108:109], v[96:97], v[72:73]
	v_pk_fma_f32 v[174:175], v[110:111], v[94:95], v[70:71]
	v_pk_fma_f32 v[178:179], v[110:111], v[98:99], v[74:75]
	v_pk_fma_f32 v[100:101], v[112:113], v[96:97], v[172:173] neg_lo:[1,0,0] neg_hi:[1,0,0]
	v_pk_fma_f32 v[104:105], v[112:113], v[92:93], v[176:177]
	v_pk_fma_f32 v[102:103], v[114:115], v[98:99], v[174:175] neg_lo:[1,0,0] neg_hi:[1,0,0]
	v_pk_fma_f32 v[106:107], v[114:115], v[94:95], v[178:179]
	global_load_dwordx4 v[68:71], v50, s[6:7]
	global_load_dwordx4 v[72:75], v50, s[6:7] offset:256
	v_add_u32_e32 v50, v50, v116
	v_cvt_pk_bf16_f32 v184, v100, v101
	v_cvt_pk_bf16_f32 v185, v102, v103
	v_cvt_pk_bf16_f32 v186, v104, v105
	v_cvt_pk_bf16_f32 v187, v106, v107
	global_store_dwordx2 v51, v[184:185], s[8:9]
	global_store_dwordx2 v51, v[186:187], s[8:9] offset:128
	v_add_u32_e32 v51, v51, v117
	s_waitcnt vmcnt(42)
	v_pk_fma_f32 v[172:173], v[108:109], v[100:101], v[76:77]
	v_pk_fma_f32 v[176:177], v[108:109], v[104:105], v[80:81]
	v_pk_fma_f32 v[174:175], v[110:111], v[102:103], v[78:79]
	v_pk_fma_f32 v[178:179], v[110:111], v[106:107], v[82:83]
	v_pk_fma_f32 v[92:93], v[112:113], v[104:105], v[172:173] neg_lo:[1,0,0] neg_hi:[1,0,0]
	v_pk_fma_f32 v[96:97], v[112:113], v[100:101], v[176:177]
	v_pk_fma_f32 v[94:95], v[114:115], v[106:107], v[174:175] neg_lo:[1,0,0] neg_hi:[1,0,0]
	v_pk_fma_f32 v[98:99], v[114:115], v[102:103], v[178:179]
	global_load_dwordx4 v[76:79], v50, s[6:7]
	global_load_dwordx4 v[80:83], v50, s[6:7] offset:256
	v_add_u32_e32 v50, v50, v116
	v_cvt_pk_bf16_f32 v180, v92, v93
	v_cvt_pk_bf16_f32 v181, v94, v95
	v_cvt_pk_bf16_f32 v182, v96, v97
	v_cvt_pk_bf16_f32 v183, v98, v99
	global_store_dwordx2 v51, v[180:181], s[8:9]
	global_store_dwordx2 v51, v[182:183], s[8:9] offset:128
	v_add_u32_e32 v51, v51, v117
	s_waitcnt vmcnt(42)
	v_pk_fma_f32 v[172:173], v[108:109], v[92:93], v[84:85]
	v_pk_fma_f32 v[176:177], v[108:109], v[96:97], v[88:89]
	v_pk_fma_f32 v[174:175], v[110:111], v[94:95], v[86:87]
	v_pk_fma_f32 v[178:179], v[110:111], v[98:99], v[90:91]
	v_pk_fma_f32 v[100:101], v[112:113], v[96:97], v[172:173] neg_lo:[1,0,0] neg_hi:[1,0,0]
	v_pk_fma_f32 v[104:105], v[112:113], v[92:93], v[176:177]
	v_pk_fma_f32 v[102:103], v[114:115], v[98:99], v[174:175] neg_lo:[1,0,0] neg_hi:[1,0,0]
	v_pk_fma_f32 v[106:107], v[114:115], v[94:95], v[178:179]
	global_load_dwordx4 v[84:87], v50, s[6:7]
	global_load_dwordx4 v[88:91], v50, s[6:7] offset:256
	v_add_u32_e32 v50, v50, v116
	v_cvt_pk_bf16_f32 v184, v100, v101
	v_cvt_pk_bf16_f32 v185, v102, v103
	v_cvt_pk_bf16_f32 v186, v104, v105
	v_cvt_pk_bf16_f32 v187, v106, v107
	global_store_dwordx2 v51, v[184:185], s[8:9]
	global_store_dwordx2 v51, v[186:187], s[8:9] offset:128
	v_add_u32_e32 v51, v51, v117
	s_waitcnt vmcnt(42)
	v_pk_fma_f32 v[172:173], v[108:109], v[100:101], v[0:1]
	v_pk_fma_f32 v[176:177], v[108:109], v[104:105], v[4:5]
	v_pk_fma_f32 v[174:175], v[110:111], v[102:103], v[2:3]
	v_pk_fma_f32 v[178:179], v[110:111], v[106:107], v[6:7]
	v_pk_fma_f32 v[92:93], v[112:113], v[104:105], v[172:173] neg_lo:[1,0,0] neg_hi:[1,0,0]
	v_pk_fma_f32 v[96:97], v[112:113], v[100:101], v[176:177]
	v_pk_fma_f32 v[94:95], v[114:115], v[106:107], v[174:175] neg_lo:[1,0,0] neg_hi:[1,0,0]
	v_pk_fma_f32 v[98:99], v[114:115], v[102:103], v[178:179]
	global_load_dwordx4 v[0:3], v50, s[6:7]
	global_load_dwordx4 v[4:7], v50, s[6:7] offset:256
	v_add_u32_e32 v50, v50, v116
	v_cvt_pk_bf16_f32 v180, v92, v93
	v_cvt_pk_bf16_f32 v181, v94, v95
	v_cvt_pk_bf16_f32 v182, v96, v97
	v_cvt_pk_bf16_f32 v183, v98, v99
	global_store_dwordx2 v51, v[180:181], s[8:9]
	global_store_dwordx2 v51, v[182:183], s[8:9] offset:128
	v_add_u32_e32 v51, v51, v117
	s_waitcnt vmcnt(42)
	v_pk_fma_f32 v[172:173], v[108:109], v[92:93], v[8:9]
	v_pk_fma_f32 v[176:177], v[108:109], v[96:97], v[12:13]
	v_pk_fma_f32 v[174:175], v[110:111], v[94:95], v[10:11]
	v_pk_fma_f32 v[178:179], v[110:111], v[98:99], v[14:15]
	v_pk_fma_f32 v[100:101], v[112:113], v[96:97], v[172:173] neg_lo:[1,0,0] neg_hi:[1,0,0]
	v_pk_fma_f32 v[104:105], v[112:113], v[92:93], v[176:177]
	v_pk_fma_f32 v[102:103], v[114:115], v[98:99], v[174:175] neg_lo:[1,0,0] neg_hi:[1,0,0]
	v_pk_fma_f32 v[106:107], v[114:115], v[94:95], v[178:179]
	global_load_dwordx4 v[8:11], v50, s[6:7]
	global_load_dwordx4 v[12:15], v50, s[6:7] offset:256
	v_add_u32_e32 v50, v50, v116
	v_cvt_pk_bf16_f32 v184, v100, v101
	v_cvt_pk_bf16_f32 v185, v102, v103
	v_cvt_pk_bf16_f32 v186, v104, v105
	v_cvt_pk_bf16_f32 v187, v106, v107
	global_store_dwordx2 v51, v[184:185], s[8:9]
	global_store_dwordx2 v51, v[186:187], s[8:9] offset:128
	v_add_u32_e32 v51, v51, v117
	s_waitcnt vmcnt(42)
	v_pk_fma_f32 v[172:173], v[108:109], v[100:101], v[16:17]
	v_pk_fma_f32 v[176:177], v[108:109], v[104:105], v[20:21]
	v_pk_fma_f32 v[174:175], v[110:111], v[102:103], v[18:19]
	v_pk_fma_f32 v[178:179], v[110:111], v[106:107], v[22:23]
	v_pk_fma_f32 v[92:93], v[112:113], v[104:105], v[172:173] neg_lo:[1,0,0] neg_hi:[1,0,0]
	v_pk_fma_f32 v[96:97], v[112:113], v[100:101], v[176:177]
	v_pk_fma_f32 v[94:95], v[114:115], v[106:107], v[174:175] neg_lo:[1,0,0] neg_hi:[1,0,0]
	v_pk_fma_f32 v[98:99], v[114:115], v[102:103], v[178:179]
	global_load_dwordx4 v[16:19], v50, s[6:7]
	global_load_dwordx4 v[20:23], v50, s[6:7] offset:256
	v_add_u32_e32 v50, v50, v116
	v_cvt_pk_bf16_f32 v180, v92, v93
	v_cvt_pk_bf16_f32 v181, v94, v95
	v_cvt_pk_bf16_f32 v182, v96, v97
	v_cvt_pk_bf16_f32 v183, v98, v99
	global_store_dwordx2 v51, v[180:181], s[8:9]
	global_store_dwordx2 v51, v[182:183], s[8:9] offset:128
	v_add_u32_e32 v51, v51, v117
	s_waitcnt vmcnt(42)
	v_pk_fma_f32 v[172:173], v[108:109], v[92:93], v[24:25]
	v_pk_fma_f32 v[176:177], v[108:109], v[96:97], v[28:29]
	v_pk_fma_f32 v[174:175], v[110:111], v[94:95], v[26:27]
	v_pk_fma_f32 v[178:179], v[110:111], v[98:99], v[30:31]
	v_pk_fma_f32 v[100:101], v[112:113], v[96:97], v[172:173] neg_lo:[1,0,0] neg_hi:[1,0,0]
	v_pk_fma_f32 v[104:105], v[112:113], v[92:93], v[176:177]
	v_pk_fma_f32 v[102:103], v[114:115], v[98:99], v[174:175] neg_lo:[1,0,0] neg_hi:[1,0,0]
	v_pk_fma_f32 v[106:107], v[114:115], v[94:95], v[178:179]
	global_load_dwordx4 v[24:27], v50, s[6:7]
	global_load_dwordx4 v[28:31], v50, s[6:7] offset:256
	v_add_u32_e32 v50, v50, v116
	v_cvt_pk_bf16_f32 v184, v100, v101
	v_cvt_pk_bf16_f32 v185, v102, v103
	v_cvt_pk_bf16_f32 v186, v104, v105
	v_cvt_pk_bf16_f32 v187, v106, v107
	global_store_dwordx2 v51, v[184:185], s[8:9]
	global_store_dwordx2 v51, v[186:187], s[8:9] offset:128
	v_add_u32_e32 v51, v51, v117
	s_waitcnt vmcnt(42)
	v_pk_fma_f32 v[172:173], v[108:109], v[100:101], v[32:33]
	v_pk_fma_f32 v[176:177], v[108:109], v[104:105], v[36:37]
	v_pk_fma_f32 v[174:175], v[110:111], v[102:103], v[34:35]
	v_pk_fma_f32 v[178:179], v[110:111], v[106:107], v[38:39]
	v_pk_fma_f32 v[92:93], v[112:113], v[104:105], v[172:173] neg_lo:[1,0,0] neg_hi:[1,0,0]
	v_pk_fma_f32 v[96:97], v[112:113], v[100:101], v[176:177]
	v_pk_fma_f32 v[94:95], v[114:115], v[106:107], v[174:175] neg_lo:[1,0,0] neg_hi:[1,0,0]
	v_pk_fma_f32 v[98:99], v[114:115], v[102:103], v[178:179]
	global_load_dwordx4 v[32:35], v50, s[6:7]
	global_load_dwordx4 v[36:39], v50, s[6:7] offset:256
	v_add_u32_e32 v50, v50, v116
	v_cvt_pk_bf16_f32 v180, v92, v93
	v_cvt_pk_bf16_f32 v181, v94, v95
	v_cvt_pk_bf16_f32 v182, v96, v97
	v_cvt_pk_bf16_f32 v183, v98, v99
	global_store_dwordx2 v51, v[180:181], s[8:9]
	global_store_dwordx2 v51, v[182:183], s[8:9] offset:128
	v_add_u32_e32 v51, v51, v117
	s_waitcnt vmcnt(42)
	v_pk_fma_f32 v[172:173], v[108:109], v[92:93], v[40:41]
	v_pk_fma_f32 v[176:177], v[108:109], v[96:97], v[44:45]
	v_pk_fma_f32 v[174:175], v[110:111], v[94:95], v[42:43]
	v_pk_fma_f32 v[178:179], v[110:111], v[98:99], v[46:47]
	v_pk_fma_f32 v[100:101], v[112:113], v[96:97], v[172:173] neg_lo:[1,0,0] neg_hi:[1,0,0]
	v_pk_fma_f32 v[104:105], v[112:113], v[92:93], v[176:177]
	v_pk_fma_f32 v[102:103], v[114:115], v[98:99], v[174:175] neg_lo:[1,0,0] neg_hi:[1,0,0]
	v_pk_fma_f32 v[106:107], v[114:115], v[94:95], v[178:179]
	global_load_dwordx4 v[40:43], v50, s[6:7]
	global_load_dwordx4 v[44:47], v50, s[6:7] offset:256
	v_add_u32_e32 v50, v50, v116
	v_cvt_pk_bf16_f32 v184, v100, v101
	v_cvt_pk_bf16_f32 v185, v102, v103
	v_cvt_pk_bf16_f32 v186, v104, v105
	v_cvt_pk_bf16_f32 v187, v106, v107
	global_store_dwordx2 v51, v[184:185], s[8:9]
	global_store_dwordx2 v51, v[186:187], s[8:9] offset:128
	v_add_u32_e32 v51, v51, v117
	s_waitcnt vmcnt(42)
	v_pk_fma_f32 v[172:173], v[108:109], v[100:101], v[52:53]
	v_pk_fma_f32 v[176:177], v[108:109], v[104:105], v[56:57]
	v_pk_fma_f32 v[174:175], v[110:111], v[102:103], v[54:55]
	v_pk_fma_f32 v[178:179], v[110:111], v[106:107], v[58:59]
	v_pk_fma_f32 v[92:93], v[112:113], v[104:105], v[172:173] neg_lo:[1,0,0] neg_hi:[1,0,0]
	v_pk_fma_f32 v[96:97], v[112:113], v[100:101], v[176:177]
	v_pk_fma_f32 v[94:95], v[114:115], v[106:107], v[174:175] neg_lo:[1,0,0] neg_hi:[1,0,0]
	v_pk_fma_f32 v[98:99], v[114:115], v[102:103], v[178:179]
	global_load_dwordx4 v[52:55], v50, s[6:7]
	global_load_dwordx4 v[56:59], v50, s[6:7] offset:256
	v_add_u32_e32 v50, v50, v116
	v_cvt_pk_bf16_f32 v180, v92, v93
	v_cvt_pk_bf16_f32 v181, v94, v95
	v_cvt_pk_bf16_f32 v182, v96, v97
	v_cvt_pk_bf16_f32 v183, v98, v99
	global_store_dwordx2 v51, v[180:181], s[8:9]
	global_store_dwordx2 v51, v[182:183], s[8:9] offset:128
	v_add_u32_e32 v51, v51, v117
	s_waitcnt vmcnt(42)
	v_pk_fma_f32 v[172:173], v[108:109], v[92:93], v[60:61]
	v_pk_fma_f32 v[176:177], v[108:109], v[96:97], v[64:65]
	v_pk_fma_f32 v[174:175], v[110:111], v[94:95], v[62:63]
	v_pk_fma_f32 v[178:179], v[110:111], v[98:99], v[66:67]
	v_pk_fma_f32 v[100:101], v[112:113], v[96:97], v[172:173] neg_lo:[1,0,0] neg_hi:[1,0,0]
	v_pk_fma_f32 v[104:105], v[112:113], v[92:93], v[176:177]
	v_pk_fma_f32 v[102:103], v[114:115], v[98:99], v[174:175] neg_lo:[1,0,0] neg_hi:[1,0,0]
	v_pk_fma_f32 v[106:107], v[114:115], v[94:95], v[178:179]
	global_load_dwordx4 v[60:63], v50, s[6:7]
	global_load_dwordx4 v[64:67], v50, s[6:7] offset:256
	v_add_u32_e32 v50, v50, v116
	v_cvt_pk_bf16_f32 v184, v100, v101
	v_cvt_pk_bf16_f32 v185, v102, v103
	v_cvt_pk_bf16_f32 v186, v104, v105
	v_cvt_pk_bf16_f32 v187, v106, v107
	global_store_dwordx2 v51, v[184:185], s[8:9]
	global_store_dwordx2 v51, v[186:187], s[8:9] offset:128
	v_add_u32_e32 v51, v51, v117
	s_waitcnt vmcnt(42)
	v_pk_fma_f32 v[172:173], v[108:109], v[100:101], v[68:69]
	v_pk_fma_f32 v[176:177], v[108:109], v[104:105], v[72:73]
	v_pk_fma_f32 v[174:175], v[110:111], v[102:103], v[70:71]
	v_pk_fma_f32 v[178:179], v[110:111], v[106:107], v[74:75]
	v_pk_fma_f32 v[92:93], v[112:113], v[104:105], v[172:173] neg_lo:[1,0,0] neg_hi:[1,0,0]
	v_pk_fma_f32 v[96:97], v[112:113], v[100:101], v[176:177]
	v_pk_fma_f32 v[94:95], v[114:115], v[106:107], v[174:175] neg_lo:[1,0,0] neg_hi:[1,0,0]
	v_pk_fma_f32 v[98:99], v[114:115], v[102:103], v[178:179]
	global_load_dwordx4 v[68:71], v50, s[6:7]
	global_load_dwordx4 v[72:75], v50, s[6:7] offset:256
	v_add_u32_e32 v50, v50, v116
	v_cvt_pk_bf16_f32 v180, v92, v93
	v_cvt_pk_bf16_f32 v181, v94, v95
	v_cvt_pk_bf16_f32 v182, v96, v97
	v_cvt_pk_bf16_f32 v183, v98, v99
	global_store_dwordx2 v51, v[180:181], s[8:9]
	global_store_dwordx2 v51, v[182:183], s[8:9] offset:128
	v_add_u32_e32 v51, v51, v117
	s_waitcnt vmcnt(42)
	v_pk_fma_f32 v[172:173], v[108:109], v[92:93], v[76:77]
	v_pk_fma_f32 v[176:177], v[108:109], v[96:97], v[80:81]
	v_pk_fma_f32 v[174:175], v[110:111], v[94:95], v[78:79]
	v_pk_fma_f32 v[178:179], v[110:111], v[98:99], v[82:83]
	v_pk_fma_f32 v[100:101], v[112:113], v[96:97], v[172:173] neg_lo:[1,0,0] neg_hi:[1,0,0]
	v_pk_fma_f32 v[104:105], v[112:113], v[92:93], v[176:177]
	v_pk_fma_f32 v[102:103], v[114:115], v[98:99], v[174:175] neg_lo:[1,0,0] neg_hi:[1,0,0]
	v_pk_fma_f32 v[106:107], v[114:115], v[94:95], v[178:179]
	global_load_dwordx4 v[76:79], v50, s[6:7]
	global_load_dwordx4 v[80:83], v50, s[6:7] offset:256
	v_add_u32_e32 v50, v50, v116
	v_cvt_pk_bf16_f32 v184, v100, v101
	v_cvt_pk_bf16_f32 v185, v102, v103
	v_cvt_pk_bf16_f32 v186, v104, v105
	v_cvt_pk_bf16_f32 v187, v106, v107
	global_store_dwordx2 v51, v[184:185], s[8:9]
	global_store_dwordx2 v51, v[186:187], s[8:9] offset:128
	v_add_u32_e32 v51, v51, v117
	s_waitcnt vmcnt(42)
	v_pk_fma_f32 v[172:173], v[108:109], v[100:101], v[84:85]
	v_pk_fma_f32 v[176:177], v[108:109], v[104:105], v[88:89]
	v_pk_fma_f32 v[174:175], v[110:111], v[102:103], v[86:87]
	v_pk_fma_f32 v[178:179], v[110:111], v[106:107], v[90:91]
	v_pk_fma_f32 v[92:93], v[112:113], v[104:105], v[172:173] neg_lo:[1,0,0] neg_hi:[1,0,0]
	v_pk_fma_f32 v[96:97], v[112:113], v[100:101], v[176:177]
	v_pk_fma_f32 v[94:95], v[114:115], v[106:107], v[174:175] neg_lo:[1,0,0] neg_hi:[1,0,0]
	v_pk_fma_f32 v[98:99], v[114:115], v[102:103], v[178:179]
	global_load_dwordx4 v[84:87], v50, s[6:7]
	global_load_dwordx4 v[88:91], v50, s[6:7] offset:256
	v_add_u32_e32 v50, v50, v116
	v_cvt_pk_bf16_f32 v180, v92, v93
	v_cvt_pk_bf16_f32 v181, v94, v95
	v_cvt_pk_bf16_f32 v182, v96, v97
	v_cvt_pk_bf16_f32 v183, v98, v99
	global_store_dwordx2 v51, v[180:181], s[8:9]
	global_store_dwordx2 v51, v[182:183], s[8:9] offset:128
	v_add_u32_e32 v51, v51, v117
	s_waitcnt vmcnt(42)
	v_pk_fma_f32 v[172:173], v[108:109], v[92:93], v[0:1]
	v_pk_fma_f32 v[176:177], v[108:109], v[96:97], v[4:5]
	v_pk_fma_f32 v[174:175], v[110:111], v[94:95], v[2:3]
	v_pk_fma_f32 v[178:179], v[110:111], v[98:99], v[6:7]
	v_pk_fma_f32 v[100:101], v[112:113], v[96:97], v[172:173] neg_lo:[1,0,0] neg_hi:[1,0,0]
	v_pk_fma_f32 v[104:105], v[112:113], v[92:93], v[176:177]
	v_pk_fma_f32 v[102:103], v[114:115], v[98:99], v[174:175] neg_lo:[1,0,0] neg_hi:[1,0,0]
	v_pk_fma_f32 v[106:107], v[114:115], v[94:95], v[178:179]
	global_load_dwordx4 v[0:3], v50, s[6:7]
	global_load_dwordx4 v[4:7], v50, s[6:7] offset:256
	v_add_u32_e32 v50, v50, v116
	v_cvt_pk_bf16_f32 v184, v100, v101
	v_cvt_pk_bf16_f32 v185, v102, v103
	v_cvt_pk_bf16_f32 v186, v104, v105
	v_cvt_pk_bf16_f32 v187, v106, v107
	global_store_dwordx2 v51, v[184:185], s[8:9]
	global_store_dwordx2 v51, v[186:187], s[8:9] offset:128
	v_add_u32_e32 v51, v51, v117
	s_waitcnt vmcnt(42)
	v_pk_fma_f32 v[172:173], v[108:109], v[100:101], v[8:9]
	v_pk_fma_f32 v[176:177], v[108:109], v[104:105], v[12:13]
	v_pk_fma_f32 v[174:175], v[110:111], v[102:103], v[10:11]
	v_pk_fma_f32 v[178:179], v[110:111], v[106:107], v[14:15]
	v_pk_fma_f32 v[92:93], v[112:113], v[104:105], v[172:173] neg_lo:[1,0,0] neg_hi:[1,0,0]
	v_pk_fma_f32 v[96:97], v[112:113], v[100:101], v[176:177]
	v_pk_fma_f32 v[94:95], v[114:115], v[106:107], v[174:175] neg_lo:[1,0,0] neg_hi:[1,0,0]
	v_pk_fma_f32 v[98:99], v[114:115], v[102:103], v[178:179]
	global_load_dwordx4 v[8:11], v50, s[6:7]
	global_load_dwordx4 v[12:15], v50, s[6:7] offset:256
	v_add_u32_e32 v50, v50, v116
	v_cvt_pk_bf16_f32 v180, v92, v93
	v_cvt_pk_bf16_f32 v181, v94, v95
	v_cvt_pk_bf16_f32 v182, v96, v97
	v_cvt_pk_bf16_f32 v183, v98, v99
	global_store_dwordx2 v51, v[180:181], s[8:9]
	global_store_dwordx2 v51, v[182:183], s[8:9] offset:128
	v_add_u32_e32 v51, v51, v117
	s_waitcnt vmcnt(42)
	v_pk_fma_f32 v[172:173], v[108:109], v[92:93], v[16:17]
	v_pk_fma_f32 v[176:177], v[108:109], v[96:97], v[20:21]
	v_pk_fma_f32 v[174:175], v[110:111], v[94:95], v[18:19]
	v_pk_fma_f32 v[178:179], v[110:111], v[98:99], v[22:23]
	v_pk_fma_f32 v[100:101], v[112:113], v[96:97], v[172:173] neg_lo:[1,0,0] neg_hi:[1,0,0]
	v_pk_fma_f32 v[104:105], v[112:113], v[92:93], v[176:177]
	v_pk_fma_f32 v[102:103], v[114:115], v[98:99], v[174:175] neg_lo:[1,0,0] neg_hi:[1,0,0]
	v_pk_fma_f32 v[106:107], v[114:115], v[94:95], v[178:179]
	global_load_dwordx4 v[16:19], v50, s[6:7]
	global_load_dwordx4 v[20:23], v50, s[6:7] offset:256
	v_add_u32_e32 v50, v50, v116
	v_cvt_pk_bf16_f32 v184, v100, v101
	v_cvt_pk_bf16_f32 v185, v102, v103
	v_cvt_pk_bf16_f32 v186, v104, v105
	v_cvt_pk_bf16_f32 v187, v106, v107
	global_store_dwordx2 v51, v[184:185], s[8:9]
	global_store_dwordx2 v51, v[186:187], s[8:9] offset:128
	v_add_u32_e32 v51, v51, v117
	s_waitcnt vmcnt(42)
	v_pk_fma_f32 v[172:173], v[108:109], v[100:101], v[24:25]
	v_pk_fma_f32 v[176:177], v[108:109], v[104:105], v[28:29]
	v_pk_fma_f32 v[174:175], v[110:111], v[102:103], v[26:27]
	v_pk_fma_f32 v[178:179], v[110:111], v[106:107], v[30:31]
	v_pk_fma_f32 v[92:93], v[112:113], v[104:105], v[172:173] neg_lo:[1,0,0] neg_hi:[1,0,0]
	v_pk_fma_f32 v[96:97], v[112:113], v[100:101], v[176:177]
	v_pk_fma_f32 v[94:95], v[114:115], v[106:107], v[174:175] neg_lo:[1,0,0] neg_hi:[1,0,0]
	v_pk_fma_f32 v[98:99], v[114:115], v[102:103], v[178:179]
	global_load_dwordx4 v[24:27], v50, s[6:7]
	global_load_dwordx4 v[28:31], v50, s[6:7] offset:256
	v_add_u32_e32 v50, v50, v116
	v_cvt_pk_bf16_f32 v180, v92, v93
	v_cvt_pk_bf16_f32 v181, v94, v95
	v_cvt_pk_bf16_f32 v182, v96, v97
	v_cvt_pk_bf16_f32 v183, v98, v99
	global_store_dwordx2 v51, v[180:181], s[8:9]
	global_store_dwordx2 v51, v[182:183], s[8:9] offset:128
	v_add_u32_e32 v51, v51, v117
	s_waitcnt vmcnt(42)
	v_pk_fma_f32 v[172:173], v[108:109], v[92:93], v[32:33]
	v_pk_fma_f32 v[176:177], v[108:109], v[96:97], v[36:37]
	v_pk_fma_f32 v[174:175], v[110:111], v[94:95], v[34:35]
	v_pk_fma_f32 v[178:179], v[110:111], v[98:99], v[38:39]
	v_pk_fma_f32 v[100:101], v[112:113], v[96:97], v[172:173] neg_lo:[1,0,0] neg_hi:[1,0,0]
	v_pk_fma_f32 v[104:105], v[112:113], v[92:93], v[176:177]
	v_pk_fma_f32 v[102:103], v[114:115], v[98:99], v[174:175] neg_lo:[1,0,0] neg_hi:[1,0,0]
	v_pk_fma_f32 v[106:107], v[114:115], v[94:95], v[178:179]
	global_load_dwordx4 v[32:35], v50, s[6:7]
	global_load_dwordx4 v[36:39], v50, s[6:7] offset:256
	v_add_u32_e32 v50, v50, v116
	v_cvt_pk_bf16_f32 v184, v100, v101
	v_cvt_pk_bf16_f32 v185, v102, v103
	v_cvt_pk_bf16_f32 v186, v104, v105
	v_cvt_pk_bf16_f32 v187, v106, v107
	global_store_dwordx2 v51, v[184:185], s[8:9]
	global_store_dwordx2 v51, v[186:187], s[8:9] offset:128
	v_add_u32_e32 v51, v51, v117
	s_waitcnt vmcnt(42)
	v_pk_fma_f32 v[172:173], v[108:109], v[100:101], v[40:41]
	v_pk_fma_f32 v[176:177], v[108:109], v[104:105], v[44:45]
	v_pk_fma_f32 v[174:175], v[110:111], v[102:103], v[42:43]
	v_pk_fma_f32 v[178:179], v[110:111], v[106:107], v[46:47]
	v_pk_fma_f32 v[92:93], v[112:113], v[104:105], v[172:173] neg_lo:[1,0,0] neg_hi:[1,0,0]
	v_pk_fma_f32 v[96:97], v[112:113], v[100:101], v[176:177]
	v_pk_fma_f32 v[94:95], v[114:115], v[106:107], v[174:175] neg_lo:[1,0,0] neg_hi:[1,0,0]
	v_pk_fma_f32 v[98:99], v[114:115], v[102:103], v[178:179]
	global_load_dwordx4 v[40:43], v50, s[6:7]
	global_load_dwordx4 v[44:47], v50, s[6:7] offset:256
	v_add_u32_e32 v50, v50, v116
	v_cvt_pk_bf16_f32 v180, v92, v93
	v_cvt_pk_bf16_f32 v181, v94, v95
	v_cvt_pk_bf16_f32 v182, v96, v97
	v_cvt_pk_bf16_f32 v183, v98, v99
	global_store_dwordx2 v51, v[180:181], s[8:9]
	global_store_dwordx2 v51, v[182:183], s[8:9] offset:128
	v_add_u32_e32 v51, v51, v117
	s_waitcnt vmcnt(42)
	v_pk_fma_f32 v[172:173], v[108:109], v[92:93], v[52:53]
	v_pk_fma_f32 v[176:177], v[108:109], v[96:97], v[56:57]
	v_pk_fma_f32 v[174:175], v[110:111], v[94:95], v[54:55]
	v_pk_fma_f32 v[178:179], v[110:111], v[98:99], v[58:59]
	v_pk_fma_f32 v[100:101], v[112:113], v[96:97], v[172:173] neg_lo:[1,0,0] neg_hi:[1,0,0]
	v_pk_fma_f32 v[104:105], v[112:113], v[92:93], v[176:177]
	v_pk_fma_f32 v[102:103], v[114:115], v[98:99], v[174:175] neg_lo:[1,0,0] neg_hi:[1,0,0]
	v_pk_fma_f32 v[106:107], v[114:115], v[94:95], v[178:179]
	global_load_dwordx4 v[52:55], v50, s[6:7]
	global_load_dwordx4 v[56:59], v50, s[6:7] offset:256
	v_add_u32_e32 v50, v50, v116
	v_cvt_pk_bf16_f32 v184, v100, v101
	v_cvt_pk_bf16_f32 v185, v102, v103
	v_cvt_pk_bf16_f32 v186, v104, v105
	v_cvt_pk_bf16_f32 v187, v106, v107
	global_store_dwordx2 v51, v[184:185], s[8:9]
	global_store_dwordx2 v51, v[186:187], s[8:9] offset:128
	v_add_u32_e32 v51, v51, v117
	s_waitcnt vmcnt(42)
	v_pk_fma_f32 v[172:173], v[108:109], v[100:101], v[60:61]
	v_pk_fma_f32 v[176:177], v[108:109], v[104:105], v[64:65]
	v_pk_fma_f32 v[174:175], v[110:111], v[102:103], v[62:63]
	v_pk_fma_f32 v[178:179], v[110:111], v[106:107], v[66:67]
	v_pk_fma_f32 v[92:93], v[112:113], v[104:105], v[172:173] neg_lo:[1,0,0] neg_hi:[1,0,0]
	v_pk_fma_f32 v[96:97], v[112:113], v[100:101], v[176:177]
	v_pk_fma_f32 v[94:95], v[114:115], v[106:107], v[174:175] neg_lo:[1,0,0] neg_hi:[1,0,0]
	v_pk_fma_f32 v[98:99], v[114:115], v[102:103], v[178:179]
	global_load_dwordx4 v[60:63], v50, s[6:7]
	global_load_dwordx4 v[64:67], v50, s[6:7] offset:256
	v_add_u32_e32 v50, v50, v116
	v_cvt_pk_bf16_f32 v180, v92, v93
	v_cvt_pk_bf16_f32 v181, v94, v95
	v_cvt_pk_bf16_f32 v182, v96, v97
	v_cvt_pk_bf16_f32 v183, v98, v99
	global_store_dwordx2 v51, v[180:181], s[8:9]
	global_store_dwordx2 v51, v[182:183], s[8:9] offset:128
	v_add_u32_e32 v51, v51, v117
	s_waitcnt vmcnt(42)
	v_pk_fma_f32 v[172:173], v[108:109], v[92:93], v[68:69]
	v_pk_fma_f32 v[176:177], v[108:109], v[96:97], v[72:73]
	v_pk_fma_f32 v[174:175], v[110:111], v[94:95], v[70:71]
	v_pk_fma_f32 v[178:179], v[110:111], v[98:99], v[74:75]
	v_pk_fma_f32 v[100:101], v[112:113], v[96:97], v[172:173] neg_lo:[1,0,0] neg_hi:[1,0,0]
	v_pk_fma_f32 v[104:105], v[112:113], v[92:93], v[176:177]
	v_pk_fma_f32 v[102:103], v[114:115], v[98:99], v[174:175] neg_lo:[1,0,0] neg_hi:[1,0,0]
	v_pk_fma_f32 v[106:107], v[114:115], v[94:95], v[178:179]
	global_load_dwordx4 v[68:71], v50, s[6:7]
	global_load_dwordx4 v[72:75], v50, s[6:7] offset:256
	v_add_u32_e32 v50, v50, v116
	v_cvt_pk_bf16_f32 v184, v100, v101
	v_cvt_pk_bf16_f32 v185, v102, v103
	v_cvt_pk_bf16_f32 v186, v104, v105
	v_cvt_pk_bf16_f32 v187, v106, v107
	global_store_dwordx2 v51, v[184:185], s[8:9]
	global_store_dwordx2 v51, v[186:187], s[8:9] offset:128
	v_add_u32_e32 v51, v51, v117
	s_waitcnt vmcnt(42)
	v_pk_fma_f32 v[172:173], v[108:109], v[100:101], v[76:77]
	v_pk_fma_f32 v[176:177], v[108:109], v[104:105], v[80:81]
	v_pk_fma_f32 v[174:175], v[110:111], v[102:103], v[78:79]
	v_pk_fma_f32 v[178:179], v[110:111], v[106:107], v[82:83]
	v_pk_fma_f32 v[92:93], v[112:113], v[104:105], v[172:173] neg_lo:[1,0,0] neg_hi:[1,0,0]
	v_pk_fma_f32 v[96:97], v[112:113], v[100:101], v[176:177]
	v_pk_fma_f32 v[94:95], v[114:115], v[106:107], v[174:175] neg_lo:[1,0,0] neg_hi:[1,0,0]
	v_pk_fma_f32 v[98:99], v[114:115], v[102:103], v[178:179]
	global_load_dwordx4 v[76:79], v50, s[6:7]
	global_load_dwordx4 v[80:83], v50, s[6:7] offset:256
	v_add_u32_e32 v50, v50, v116
	v_cvt_pk_bf16_f32 v180, v92, v93
	v_cvt_pk_bf16_f32 v181, v94, v95
	v_cvt_pk_bf16_f32 v182, v96, v97
	v_cvt_pk_bf16_f32 v183, v98, v99
	global_store_dwordx2 v51, v[180:181], s[8:9]
	global_store_dwordx2 v51, v[182:183], s[8:9] offset:128
	v_add_u32_e32 v51, v51, v117
	s_waitcnt vmcnt(42)
	v_pk_fma_f32 v[172:173], v[108:109], v[92:93], v[84:85]
	v_pk_fma_f32 v[176:177], v[108:109], v[96:97], v[88:89]
	v_pk_fma_f32 v[174:175], v[110:111], v[94:95], v[86:87]
	v_pk_fma_f32 v[178:179], v[110:111], v[98:99], v[90:91]
	v_pk_fma_f32 v[100:101], v[112:113], v[96:97], v[172:173] neg_lo:[1,0,0] neg_hi:[1,0,0]
	v_pk_fma_f32 v[104:105], v[112:113], v[92:93], v[176:177]
	v_pk_fma_f32 v[102:103], v[114:115], v[98:99], v[174:175] neg_lo:[1,0,0] neg_hi:[1,0,0]
	v_pk_fma_f32 v[106:107], v[114:115], v[94:95], v[178:179]
	global_load_dwordx4 v[84:87], v50, s[6:7]
	global_load_dwordx4 v[88:91], v50, s[6:7] offset:256
	v_add_u32_e32 v50, v50, v116
	v_cvt_pk_bf16_f32 v184, v100, v101
	v_cvt_pk_bf16_f32 v185, v102, v103
	v_cvt_pk_bf16_f32 v186, v104, v105
	v_cvt_pk_bf16_f32 v187, v106, v107
	global_store_dwordx2 v51, v[184:185], s[8:9]
	global_store_dwordx2 v51, v[186:187], s[8:9] offset:128
	v_add_u32_e32 v51, v51, v117
	s_waitcnt vmcnt(42)
	v_pk_fma_f32 v[172:173], v[108:109], v[100:101], v[0:1]
	v_pk_fma_f32 v[176:177], v[108:109], v[104:105], v[4:5]
	v_pk_fma_f32 v[174:175], v[110:111], v[102:103], v[2:3]
	v_pk_fma_f32 v[178:179], v[110:111], v[106:107], v[6:7]
	v_pk_fma_f32 v[92:93], v[112:113], v[104:105], v[172:173] neg_lo:[1,0,0] neg_hi:[1,0,0]
	v_pk_fma_f32 v[96:97], v[112:113], v[100:101], v[176:177]
	v_pk_fma_f32 v[94:95], v[114:115], v[106:107], v[174:175] neg_lo:[1,0,0] neg_hi:[1,0,0]
	v_pk_fma_f32 v[98:99], v[114:115], v[102:103], v[178:179]
	global_load_dwordx4 v[0:3], v50, s[6:7]
	global_load_dwordx4 v[4:7], v50, s[6:7] offset:256
	v_add_u32_e32 v50, v50, v116
	v_cvt_pk_bf16_f32 v180, v92, v93
	v_cvt_pk_bf16_f32 v181, v94, v95
	v_cvt_pk_bf16_f32 v182, v96, v97
	v_cvt_pk_bf16_f32 v183, v98, v99
	global_store_dwordx2 v51, v[180:181], s[8:9]
	global_store_dwordx2 v51, v[182:183], s[8:9] offset:128
	v_add_u32_e32 v51, v51, v117
	s_waitcnt vmcnt(42)
	v_pk_fma_f32 v[172:173], v[108:109], v[92:93], v[8:9]
	v_pk_fma_f32 v[176:177], v[108:109], v[96:97], v[12:13]
	v_pk_fma_f32 v[174:175], v[110:111], v[94:95], v[10:11]
	v_pk_fma_f32 v[178:179], v[110:111], v[98:99], v[14:15]
	v_pk_fma_f32 v[100:101], v[112:113], v[96:97], v[172:173] neg_lo:[1,0,0] neg_hi:[1,0,0]
	v_pk_fma_f32 v[104:105], v[112:113], v[92:93], v[176:177]
	v_pk_fma_f32 v[102:103], v[114:115], v[98:99], v[174:175] neg_lo:[1,0,0] neg_hi:[1,0,0]
	v_pk_fma_f32 v[106:107], v[114:115], v[94:95], v[178:179]
	global_load_dwordx4 v[8:11], v50, s[6:7]
	global_load_dwordx4 v[12:15], v50, s[6:7] offset:256
	v_add_u32_e32 v50, v50, v116
	v_cvt_pk_bf16_f32 v184, v100, v101
	v_cvt_pk_bf16_f32 v185, v102, v103
	v_cvt_pk_bf16_f32 v186, v104, v105
	v_cvt_pk_bf16_f32 v187, v106, v107
	global_store_dwordx2 v51, v[184:185], s[8:9]
	global_store_dwordx2 v51, v[186:187], s[8:9] offset:128
	v_add_u32_e32 v51, v51, v117
	s_waitcnt vmcnt(42)
	v_pk_fma_f32 v[172:173], v[108:109], v[100:101], v[16:17]
	v_pk_fma_f32 v[176:177], v[108:109], v[104:105], v[20:21]
	v_pk_fma_f32 v[174:175], v[110:111], v[102:103], v[18:19]
	v_pk_fma_f32 v[178:179], v[110:111], v[106:107], v[22:23]
	v_pk_fma_f32 v[92:93], v[112:113], v[104:105], v[172:173] neg_lo:[1,0,0] neg_hi:[1,0,0]
	v_pk_fma_f32 v[96:97], v[112:113], v[100:101], v[176:177]
	v_pk_fma_f32 v[94:95], v[114:115], v[106:107], v[174:175] neg_lo:[1,0,0] neg_hi:[1,0,0]
	v_pk_fma_f32 v[98:99], v[114:115], v[102:103], v[178:179]
	global_load_dwordx4 v[16:19], v50, s[6:7]
	global_load_dwordx4 v[20:23], v50, s[6:7] offset:256
	v_add_u32_e32 v50, v50, v116
	v_cvt_pk_bf16_f32 v180, v92, v93
	v_cvt_pk_bf16_f32 v181, v94, v95
	v_cvt_pk_bf16_f32 v182, v96, v97
	v_cvt_pk_bf16_f32 v183, v98, v99
	global_store_dwordx2 v51, v[180:181], s[8:9]
	global_store_dwordx2 v51, v[182:183], s[8:9] offset:128
	v_add_u32_e32 v51, v51, v117
	s_waitcnt vmcnt(42)
	v_pk_fma_f32 v[172:173], v[108:109], v[92:93], v[24:25]
	v_pk_fma_f32 v[176:177], v[108:109], v[96:97], v[28:29]
	v_pk_fma_f32 v[174:175], v[110:111], v[94:95], v[26:27]
	v_pk_fma_f32 v[178:179], v[110:111], v[98:99], v[30:31]
	v_pk_fma_f32 v[100:101], v[112:113], v[96:97], v[172:173] neg_lo:[1,0,0] neg_hi:[1,0,0]
	v_pk_fma_f32 v[104:105], v[112:113], v[92:93], v[176:177]
	v_pk_fma_f32 v[102:103], v[114:115], v[98:99], v[174:175] neg_lo:[1,0,0] neg_hi:[1,0,0]
	v_pk_fma_f32 v[106:107], v[114:115], v[94:95], v[178:179]
	global_load_dwordx4 v[24:27], v50, s[6:7]
	global_load_dwordx4 v[28:31], v50, s[6:7] offset:256
	v_add_u32_e32 v50, v50, v116
	v_cvt_pk_bf16_f32 v184, v100, v101
	v_cvt_pk_bf16_f32 v185, v102, v103
	v_cvt_pk_bf16_f32 v186, v104, v105
	v_cvt_pk_bf16_f32 v187, v106, v107
	global_store_dwordx2 v51, v[184:185], s[8:9]
	global_store_dwordx2 v51, v[186:187], s[8:9] offset:128
	v_add_u32_e32 v51, v51, v117
	s_waitcnt vmcnt(42)
	v_pk_fma_f32 v[172:173], v[108:109], v[100:101], v[32:33]
	v_pk_fma_f32 v[176:177], v[108:109], v[104:105], v[36:37]
	v_pk_fma_f32 v[174:175], v[110:111], v[102:103], v[34:35]
	v_pk_fma_f32 v[178:179], v[110:111], v[106:107], v[38:39]
	v_pk_fma_f32 v[92:93], v[112:113], v[104:105], v[172:173] neg_lo:[1,0,0] neg_hi:[1,0,0]
	v_pk_fma_f32 v[96:97], v[112:113], v[100:101], v[176:177]
	v_pk_fma_f32 v[94:95], v[114:115], v[106:107], v[174:175] neg_lo:[1,0,0] neg_hi:[1,0,0]
	v_pk_fma_f32 v[98:99], v[114:115], v[102:103], v[178:179]
	global_load_dwordx4 v[32:35], v50, s[6:7]
	global_load_dwordx4 v[36:39], v50, s[6:7] offset:256
	v_add_u32_e32 v50, v50, v116
	v_cvt_pk_bf16_f32 v180, v92, v93
	v_cvt_pk_bf16_f32 v181, v94, v95
	v_cvt_pk_bf16_f32 v182, v96, v97
	v_cvt_pk_bf16_f32 v183, v98, v99
	global_store_dwordx2 v51, v[180:181], s[8:9]
	global_store_dwordx2 v51, v[182:183], s[8:9] offset:128
	v_add_u32_e32 v51, v51, v117
	s_waitcnt vmcnt(42)
	v_pk_fma_f32 v[172:173], v[108:109], v[92:93], v[40:41]
	v_pk_fma_f32 v[176:177], v[108:109], v[96:97], v[44:45]
	v_pk_fma_f32 v[174:175], v[110:111], v[94:95], v[42:43]
	v_pk_fma_f32 v[178:179], v[110:111], v[98:99], v[46:47]
	v_pk_fma_f32 v[100:101], v[112:113], v[96:97], v[172:173] neg_lo:[1,0,0] neg_hi:[1,0,0]
	v_pk_fma_f32 v[104:105], v[112:113], v[92:93], v[176:177]
	v_pk_fma_f32 v[102:103], v[114:115], v[98:99], v[174:175] neg_lo:[1,0,0] neg_hi:[1,0,0]
	v_pk_fma_f32 v[106:107], v[114:115], v[94:95], v[178:179]
	v_cvt_pk_bf16_f32 v184, v100, v101
	v_cvt_pk_bf16_f32 v185, v102, v103
	v_cvt_pk_bf16_f32 v186, v104, v105
	v_cvt_pk_bf16_f32 v187, v106, v107
	global_store_dwordx2 v51, v[184:185], s[8:9]
	global_store_dwordx2 v51, v[186:187], s[8:9] offset:128
	v_add_u32_e32 v51, v51, v117
	s_waitcnt vmcnt(40)
	v_pk_fma_f32 v[172:173], v[108:109], v[100:101], v[52:53]
	v_pk_fma_f32 v[176:177], v[108:109], v[104:105], v[56:57]
	v_pk_fma_f32 v[174:175], v[110:111], v[102:103], v[54:55]
	v_pk_fma_f32 v[178:179], v[110:111], v[106:107], v[58:59]
	v_pk_fma_f32 v[92:93], v[112:113], v[104:105], v[172:173] neg_lo:[1,0,0] neg_hi:[1,0,0]
	v_pk_fma_f32 v[96:97], v[112:113], v[100:101], v[176:177]
	v_pk_fma_f32 v[94:95], v[114:115], v[106:107], v[174:175] neg_lo:[1,0,0] neg_hi:[1,0,0]
	v_pk_fma_f32 v[98:99], v[114:115], v[102:103], v[178:179]
	v_cvt_pk_bf16_f32 v180, v92, v93
	v_cvt_pk_bf16_f32 v181, v94, v95
	v_cvt_pk_bf16_f32 v182, v96, v97
	v_cvt_pk_bf16_f32 v183, v98, v99
	global_store_dwordx2 v51, v[180:181], s[8:9]
	global_store_dwordx2 v51, v[182:183], s[8:9] offset:128
	v_add_u32_e32 v51, v51, v117
	s_waitcnt vmcnt(38)
	v_pk_fma_f32 v[172:173], v[108:109], v[92:93], v[60:61]
	v_pk_fma_f32 v[176:177], v[108:109], v[96:97], v[64:65]
	v_pk_fma_f32 v[174:175], v[110:111], v[94:95], v[62:63]
	v_pk_fma_f32 v[178:179], v[110:111], v[98:99], v[66:67]
	v_pk_fma_f32 v[100:101], v[112:113], v[96:97], v[172:173] neg_lo:[1,0,0] neg_hi:[1,0,0]
	v_pk_fma_f32 v[104:105], v[112:113], v[92:93], v[176:177]
	v_pk_fma_f32 v[102:103], v[114:115], v[98:99], v[174:175] neg_lo:[1,0,0] neg_hi:[1,0,0]
	v_pk_fma_f32 v[106:107], v[114:115], v[94:95], v[178:179]
	v_cvt_pk_bf16_f32 v184, v100, v101
	v_cvt_pk_bf16_f32 v185, v102, v103
	v_cvt_pk_bf16_f32 v186, v104, v105
	v_cvt_pk_bf16_f32 v187, v106, v107
	global_store_dwordx2 v51, v[184:185], s[8:9]
	global_store_dwordx2 v51, v[186:187], s[8:9] offset:128
	v_add_u32_e32 v51, v51, v117
	s_waitcnt vmcnt(36)
	v_pk_fma_f32 v[172:173], v[108:109], v[100:101], v[68:69]
	v_pk_fma_f32 v[176:177], v[108:109], v[104:105], v[72:73]
	v_pk_fma_f32 v[174:175], v[110:111], v[102:103], v[70:71]
	v_pk_fma_f32 v[178:179], v[110:111], v[106:107], v[74:75]
	v_pk_fma_f32 v[92:93], v[112:113], v[104:105], v[172:173] neg_lo:[1,0,0] neg_hi:[1,0,0]
	v_pk_fma_f32 v[96:97], v[112:113], v[100:101], v[176:177]
	v_pk_fma_f32 v[94:95], v[114:115], v[106:107], v[174:175] neg_lo:[1,0,0] neg_hi:[1,0,0]
	v_pk_fma_f32 v[98:99], v[114:115], v[102:103], v[178:179]
	v_cvt_pk_bf16_f32 v180, v92, v93
	v_cvt_pk_bf16_f32 v181, v94, v95
	v_cvt_pk_bf16_f32 v182, v96, v97
	v_cvt_pk_bf16_f32 v183, v98, v99
	global_store_dwordx2 v51, v[180:181], s[8:9]
	global_store_dwordx2 v51, v[182:183], s[8:9] offset:128
	v_add_u32_e32 v51, v51, v117
	s_waitcnt vmcnt(34)
	v_pk_fma_f32 v[172:173], v[108:109], v[92:93], v[76:77]
	v_pk_fma_f32 v[176:177], v[108:109], v[96:97], v[80:81]
	v_pk_fma_f32 v[174:175], v[110:111], v[94:95], v[78:79]
	v_pk_fma_f32 v[178:179], v[110:111], v[98:99], v[82:83]
	v_pk_fma_f32 v[100:101], v[112:113], v[96:97], v[172:173] neg_lo:[1,0,0] neg_hi:[1,0,0]
	v_pk_fma_f32 v[104:105], v[112:113], v[92:93], v[176:177]
	v_pk_fma_f32 v[102:103], v[114:115], v[98:99], v[174:175] neg_lo:[1,0,0] neg_hi:[1,0,0]
	v_pk_fma_f32 v[106:107], v[114:115], v[94:95], v[178:179]
	v_cvt_pk_bf16_f32 v184, v100, v101
	v_cvt_pk_bf16_f32 v185, v102, v103
	v_cvt_pk_bf16_f32 v186, v104, v105
	v_cvt_pk_bf16_f32 v187, v106, v107
	global_store_dwordx2 v51, v[184:185], s[8:9]
	global_store_dwordx2 v51, v[186:187], s[8:9] offset:128
	v_add_u32_e32 v51, v51, v117
	s_waitcnt vmcnt(32)
	v_pk_fma_f32 v[172:173], v[108:109], v[100:101], v[84:85]
	v_pk_fma_f32 v[176:177], v[108:109], v[104:105], v[88:89]
	v_pk_fma_f32 v[174:175], v[110:111], v[102:103], v[86:87]
	v_pk_fma_f32 v[178:179], v[110:111], v[106:107], v[90:91]
	v_pk_fma_f32 v[92:93], v[112:113], v[104:105], v[172:173] neg_lo:[1,0,0] neg_hi:[1,0,0]
	v_pk_fma_f32 v[96:97], v[112:113], v[100:101], v[176:177]
	v_pk_fma_f32 v[94:95], v[114:115], v[106:107], v[174:175] neg_lo:[1,0,0] neg_hi:[1,0,0]
	v_pk_fma_f32 v[98:99], v[114:115], v[102:103], v[178:179]
	v_cvt_pk_bf16_f32 v180, v92, v93
	v_cvt_pk_bf16_f32 v181, v94, v95
	v_cvt_pk_bf16_f32 v182, v96, v97
	v_cvt_pk_bf16_f32 v183, v98, v99
	global_store_dwordx2 v51, v[180:181], s[8:9]
	global_store_dwordx2 v51, v[182:183], s[8:9] offset:128
	v_add_u32_e32 v51, v51, v117
	s_waitcnt vmcnt(30)
	v_pk_fma_f32 v[172:173], v[108:109], v[92:93], v[0:1]
	v_pk_fma_f32 v[176:177], v[108:109], v[96:97], v[4:5]
	v_pk_fma_f32 v[174:175], v[110:111], v[94:95], v[2:3]
	v_pk_fma_f32 v[178:179], v[110:111], v[98:99], v[6:7]
	v_pk_fma_f32 v[100:101], v[112:113], v[96:97], v[172:173] neg_lo:[1,0,0] neg_hi:[1,0,0]
	v_pk_fma_f32 v[104:105], v[112:113], v[92:93], v[176:177]
	v_pk_fma_f32 v[102:103], v[114:115], v[98:99], v[174:175] neg_lo:[1,0,0] neg_hi:[1,0,0]
	v_pk_fma_f32 v[106:107], v[114:115], v[94:95], v[178:179]
	v_cvt_pk_bf16_f32 v184, v100, v101
	v_cvt_pk_bf16_f32 v185, v102, v103
	v_cvt_pk_bf16_f32 v186, v104, v105
	v_cvt_pk_bf16_f32 v187, v106, v107
	global_store_dwordx2 v51, v[184:185], s[8:9]
	global_store_dwordx2 v51, v[186:187], s[8:9] offset:128
	v_add_u32_e32 v51, v51, v117
	s_waitcnt vmcnt(28)
	v_pk_fma_f32 v[172:173], v[108:109], v[100:101], v[8:9]
	v_pk_fma_f32 v[176:177], v[108:109], v[104:105], v[12:13]
	v_pk_fma_f32 v[174:175], v[110:111], v[102:103], v[10:11]
	v_pk_fma_f32 v[178:179], v[110:111], v[106:107], v[14:15]
	v_pk_fma_f32 v[92:93], v[112:113], v[104:105], v[172:173] neg_lo:[1,0,0] neg_hi:[1,0,0]
	v_pk_fma_f32 v[96:97], v[112:113], v[100:101], v[176:177]
	v_pk_fma_f32 v[94:95], v[114:115], v[106:107], v[174:175] neg_lo:[1,0,0] neg_hi:[1,0,0]
	v_pk_fma_f32 v[98:99], v[114:115], v[102:103], v[178:179]
	v_cvt_pk_bf16_f32 v180, v92, v93
	v_cvt_pk_bf16_f32 v181, v94, v95
	v_cvt_pk_bf16_f32 v182, v96, v97
	v_cvt_pk_bf16_f32 v183, v98, v99
	global_store_dwordx2 v51, v[180:181], s[8:9]
	global_store_dwordx2 v51, v[182:183], s[8:9] offset:128
	v_add_u32_e32 v51, v51, v117
	s_waitcnt vmcnt(26)
	v_pk_fma_f32 v[172:173], v[108:109], v[92:93], v[16:17]
	v_pk_fma_f32 v[176:177], v[108:109], v[96:97], v[20:21]
	v_pk_fma_f32 v[174:175], v[110:111], v[94:95], v[18:19]
	v_pk_fma_f32 v[178:179], v[110:111], v[98:99], v[22:23]
	v_pk_fma_f32 v[100:101], v[112:113], v[96:97], v[172:173] neg_lo:[1,0,0] neg_hi:[1,0,0]
	v_pk_fma_f32 v[104:105], v[112:113], v[92:93], v[176:177]
	v_pk_fma_f32 v[102:103], v[114:115], v[98:99], v[174:175] neg_lo:[1,0,0] neg_hi:[1,0,0]
	v_pk_fma_f32 v[106:107], v[114:115], v[94:95], v[178:179]
	v_cvt_pk_bf16_f32 v184, v100, v101
	v_cvt_pk_bf16_f32 v185, v102, v103
	v_cvt_pk_bf16_f32 v186, v104, v105
	v_cvt_pk_bf16_f32 v187, v106, v107
	global_store_dwordx2 v51, v[184:185], s[8:9]
	global_store_dwordx2 v51, v[186:187], s[8:9] offset:128
	v_add_u32_e32 v51, v51, v117
	s_waitcnt vmcnt(24)
	v_pk_fma_f32 v[172:173], v[108:109], v[100:101], v[24:25]
	v_pk_fma_f32 v[176:177], v[108:109], v[104:105], v[28:29]
	v_pk_fma_f32 v[174:175], v[110:111], v[102:103], v[26:27]
	v_pk_fma_f32 v[178:179], v[110:111], v[106:107], v[30:31]
	v_pk_fma_f32 v[92:93], v[112:113], v[104:105], v[172:173] neg_lo:[1,0,0] neg_hi:[1,0,0]
	v_pk_fma_f32 v[96:97], v[112:113], v[100:101], v[176:177]
	v_pk_fma_f32 v[94:95], v[114:115], v[106:107], v[174:175] neg_lo:[1,0,0] neg_hi:[1,0,0]
	v_pk_fma_f32 v[98:99], v[114:115], v[102:103], v[178:179]
	v_cvt_pk_bf16_f32 v180, v92, v93
	v_cvt_pk_bf16_f32 v181, v94, v95
	v_cvt_pk_bf16_f32 v182, v96, v97
	v_cvt_pk_bf16_f32 v183, v98, v99
	global_store_dwordx2 v51, v[180:181], s[8:9]
	global_store_dwordx2 v51, v[182:183], s[8:9] offset:128
	v_add_u32_e32 v51, v51, v117
	s_waitcnt vmcnt(22)
	v_pk_fma_f32 v[172:173], v[108:109], v[92:93], v[32:33]
	v_pk_fma_f32 v[176:177], v[108:109], v[96:97], v[36:37]
	v_pk_fma_f32 v[174:175], v[110:111], v[94:95], v[34:35]
	v_pk_fma_f32 v[178:179], v[110:111], v[98:99], v[38:39]
	v_pk_fma_f32 v[100:101], v[112:113], v[96:97], v[172:173] neg_lo:[1,0,0] neg_hi:[1,0,0]
	v_pk_fma_f32 v[104:105], v[112:113], v[92:93], v[176:177]
	v_pk_fma_f32 v[102:103], v[114:115], v[98:99], v[174:175] neg_lo:[1,0,0] neg_hi:[1,0,0]
	v_pk_fma_f32 v[106:107], v[114:115], v[94:95], v[178:179]
	v_cvt_pk_bf16_f32 v184, v100, v101
	v_cvt_pk_bf16_f32 v185, v102, v103
	v_cvt_pk_bf16_f32 v186, v104, v105
	v_cvt_pk_bf16_f32 v187, v106, v107
	global_store_dwordx2 v51, v[184:185], s[8:9]
	global_store_dwordx2 v51, v[186:187], s[8:9] offset:128
	v_add_u32_e32 v51, v51, v117
